# v7: + all 8 LDS-DMA of a K-tile issued in the LDS-read latency window at the top of each K-iteration; ffn_up tile start waits vmcnt(32) (does not wait for the previous epilogue stores)
# speedup vs baseline: 1.0491x; 1.0067x over previous
; DI int tidx() { int t = threadIdx.x; asm volatile("" : "+v"(t)); return t; }
; #define GAS __attribute__((address_space(1)))
; DI void gemm_stage(const u16* __restrict__ A, int lda, const u16* __restrict__ B, int ldb, int kt, char* sbuf) {
;   const int tid = tidx(), lane = tid & 63, wave = __builtin_amdgcn_readfirstlane(tid >> 6);
;   const int pp = lane >> 4, pos = lane & 15;
; #pragma unroll
;   for (int i = 0; i < 4; i++) {
;     const int blk = i * 4 + wave;
;     const int p = blk * 4 + pp;
;     const int row = 2 * p + (pos >> 3), c8 = (pos & 7) ^ (p & 7);
;     const u16* ga = A + (size_t)row * lda + kt * 64 + c8 * 8;
;     const u16* gb = B + (size_t)row * ldb + kt * 64 + c8 * 8;
;     __builtin_amdgcn_global_load_lds((const GAS void*)ga, (__attribute__((address_space(3))) void*)(sbuf + blk * 1024), 16, 0, 0);
;     __builtin_amdgcn_global_load_lds((const GAS void*)gb, (__attribute__((address_space(3))) void*)(sbuf + 16384 + blk * 1024), 16, 0, 0);
;   }
; }
; template <class AF, class BF, class INI, class EPI>
; DI void gemm_phase_init(int TM, int TN, int K, int lda, int ldb, AF a_of, BF b_of, INI ini, EPI epi, int bid, int nb, u16* sm) {
;   int tm, tn;
;   bool have = tile_at(0, bid, nb, TM, TN, tm, tn);
;   __syncthreads();
;   if (have) gemm_stage(a_of(tm), lda, b_of(tn), ldb, 0, (char*)sm);
.LBB0_676:
	s_andn2_b64 vcc, exec, s[10:11]
	s_barrier
	s_cbranch_vccnz .LBB0_695
	v_readlane_b32 s10, v237, 0
	v_readlane_b32 s11, v237, 1
	s_add_u32 s3, s10, s4
	s_addc_u32 s18, s11, s5
	s_add_u32 s19, s3, 0x558d140
	s_addc_u32 s20, s18, 0
	s_add_u32 s4, s3, 0x1158d140
	s_addc_u32 s5, s18, 0
	s_ashr_i32 s9, s8, 31
	s_lshl_b64 s[10:11], s[8:9], 18
	s_add_u32 s10, s19, s10
	s_addc_u32 s11, s20, s11
	s_ashr_i32 s7, s6, 31
	s_lshl_b64 s[12:13], s[6:7], 18
	v_mov_b32_e32 v1, v202
	s_add_u32 s12, s3, s12
	s_addc_u32 s13, s18, s13
	v_readfirstlane_b32 s7, v1
	s_ashr_i32 s7, s7, 6
	v_bfe_u32 v8, v1, 4, 2
	s_lshl_b32 s9, s7, 2
	v_bfe_u32 v9, v1, 3, 1
	v_or_b32_e32 v4, s9, v8
	v_lshl_or_b32 v4, v4, 1, v9
	v_bitop3_b32 v10, s9, v1, v8 bitop3:0x36
	v_ashrrev_i32_e32 v5, 31, v4
	v_lshlrev_b64 v[4:5], 11, v[4:5]
	v_lshlrev_b32_e32 v10, 4, v10
	s_lshl_b32 s9, s7, 10
	v_lshl_add_u64 v[6:7], s[10:11], 0, v[4:5]
	v_and_b32_e32 v66, 0x70, v10
	v_mov_b32_e32 v67, 0
	s_add_i32 s9, s9, 0
	v_lshl_add_u64 v[6:7], v[6:7], 0, v[66:67]
	s_mov_b32 m0, s9
	v_lshl_add_u64 v[4:5], s[12:13], 0, v[4:5]
	global_load_lds_dwordx4 v[6:7], off
	s_add_i32 m0, s9, 0x4000
	s_add_i32 s9, s7, 4
	v_lshl_add_u64 v[4:5], v[4:5], 0, v[66:67]
	s_lshl_b32 s14, s9, 2
	global_load_lds_dwordx4 v[4:5], off
	v_or_b32_e32 v4, s14, v8
	v_lshl_or_b32 v4, v4, 1, v9
	v_bitop3_b32 v10, s14, v1, v8 bitop3:0x36
	v_ashrrev_i32_e32 v5, 31, v4
	v_lshlrev_b64 v[4:5], 11, v[4:5]
	v_lshlrev_b32_e32 v10, 4, v10
	s_lshl_b32 s9, s9, 10
	v_lshl_add_u64 v[6:7], s[10:11], 0, v[4:5]
	v_and_b32_e32 v66, 0x70, v10
	s_add_i32 s9, s9, 0
	v_lshl_add_u64 v[6:7], v[6:7], 0, v[66:67]
	s_mov_b32 m0, s9
	v_lshl_add_u64 v[4:5], s[12:13], 0, v[4:5]
	global_load_lds_dwordx4 v[6:7], off
	s_add_i32 m0, s9, 0x4000
	s_add_i32 s9, s7, 8
	v_lshl_add_u64 v[4:5], v[4:5], 0, v[66:67]
	s_lshl_b32 s14, s9, 2
	global_load_lds_dwordx4 v[4:5], off
	v_or_b32_e32 v4, s14, v8
	v_lshl_or_b32 v4, v4, 1, v9
	v_bitop3_b32 v10, s14, v1, v8 bitop3:0x36
	v_ashrrev_i32_e32 v5, 31, v4
	v_lshlrev_b64 v[4:5], 11, v[4:5]
	v_lshlrev_b32_e32 v10, 4, v10
	s_lshl_b32 s9, s9, 10
	v_lshl_add_u64 v[6:7], s[10:11], 0, v[4:5]
	v_and_b32_e32 v66, 0x70, v10
	s_add_i32 s9, s9, 0
	v_lshl_add_u64 v[6:7], v[6:7], 0, v[66:67]
	v_lshl_add_u64 v[4:5], s[12:13], 0, v[4:5]
	s_mov_b32 m0, s9
	s_add_i32 s7, s7, 12
	v_lshl_add_u64 v[4:5], v[4:5], 0, v[66:67]
	global_load_lds_dwordx4 v[6:7], off
	s_add_i32 m0, s9, 0x4000
	s_lshl_b32 s9, s7, 2
	global_load_lds_dwordx4 v[4:5], off
	v_or_b32_e32 v4, s9, v8
	v_lshl_or_b32 v4, v4, 1, v9
	v_bitop3_b32 v1, s9, v1, v8 bitop3:0x36
	v_ashrrev_i32_e32 v5, 31, v4
	v_lshlrev_b64 v[4:5], 11, v[4:5]
	v_lshlrev_b32_e32 v1, 4, v1
	s_lshl_b32 s7, s7, 10
	v_lshl_add_u64 v[6:7], s[10:11], 0, v[4:5]
	v_and_b32_e32 v66, 0x70, v1
	s_add_i32 s7, s7, 0
	v_lshl_add_u64 v[6:7], v[6:7], 0, v[66:67]
	v_lshl_add_u64 v[4:5], s[12:13], 0, v[4:5]
	s_mov_b32 m0, s7
	v_lshl_add_u64 v[4:5], v[4:5], 0, v[66:67]
	global_load_lds_dwordx4 v[6:7], off
	s_add_i32 m0, s7, 0x4000
	s_lshl_b32 s7, s2, 6
	global_load_lds_dwordx4 v[4:5], off
	v_lshrrev_b32_e32 v1, 1, v3
	s_ashr_i32 s22, s2, 3
	s_ashr_i32 s23, s94, 3
	s_and_b32 s24, s7, 0x1c0
	v_and_b32_e32 v1, 32, v1
	v_and_or_b32 v1, v2, 31, v1
	v_lshrrev_b32_e32 v2, 3, v2
	s_add_u32 s25, s3, 0x558d1c0
	v_ashrrev_i32_e32 v3, 1, v3
	v_and_b32_e32 v2, 4, v2
	s_movk_i32 s7, 0xffc0
	s_addc_u32 s26, s18, 0
	v_and_or_b32 v70, v3, s7, v2
	s_add_u32 s27, s3, 0x80
	s_mov_b32 s21, 0
	v_or_b32_e32 v71, 1, v70
	v_or_b32_e32 v72, 2, v70
	v_or_b32_e32 v73, 3, v70
	v_or_b32_e32 v74, 8, v70
	v_or_b32_e32 v75, 9, v70
	v_or_b32_e32 v76, 10, v70
	v_or_b32_e32 v77, 11, v70
	v_or_b32_e32 v78, 16, v70
	v_or_b32_e32 v79, 17, v70
	v_or_b32_e32 v80, 18, v70
	v_or_b32_e32 v81, 19, v70
	v_or_b32_e32 v82, 24, v70
	v_or_b32_e32 v83, 25, v70
	v_or_b32_e32 v84, 26, v70
	v_or_b32_e32 v85, 27, v70
	v_or_b32_e32 v86, 32, v70
	v_or_b32_e32 v87, 33, v70
	v_or_b32_e32 v88, 34, v70
	v_or_b32_e32 v89, 35, v70
	v_or_b32_e32 v90, 40, v70
	v_or_b32_e32 v91, 41, v70
	v_or_b32_e32 v92, 42, v70
	v_or_b32_e32 v93, 43, v70
	v_or_b32_e32 v94, 48, v70
	v_or_b32_e32 v95, 49, v70
	v_or_b32_e32 v96, 50, v70
	v_or_b32_e32 v97, 51, v70
	v_or_b32_e32 v98, 56, v70
	v_or_b32_e32 v99, 57, v70
	v_or_b32_e32 v100, 58, v70
	v_or_b32_e32 v101, 59, v70
	s_addc_u32 s28, s18, 0
	s_mov_b32 s29, 0x1ffffc0
	s_movk_i32 s30, 0x1600
	s_waitcnt vmcnt(0)
	s_branch .LBB0_679

; DI int tidx() { int t = threadIdx.x; asm volatile("" : "+v"(t)); return t; }
; DI void gemm_main(f32x16 (&acc)[2][2], const u16* __restrict__ A, int lda, const u16* __restrict__ B, int ldb, int K, u16* sm) {
;   const int tid = tidx(), lane = tid & 63, wave = tid >> 6;
;   const int wm = wave >> 1, wn = wave & 1, r = lane & 31, hh = lane >> 5;
;   char* sb = (char*)sm;
;   const int rowa = wm * 64 + r, rowb = wn * 64 + r;
;   const int baseA = (rowa >> 1) * 256 + ((rowa & 1) << 7), xa = (rowa >> 1) & 7;
;   const int baseB = 16384 + (rowb >> 1) * 256 + ((rowb & 1) << 7), xb = (rowb >> 1) & 7;
;   const int nk = K >> 6;
;   asm volatile("s_waitcnt vmcnt(0)" ::: "memory");
;   __syncthreads();
; template <class AF, class BF, class INI, class EPI>
; DI void gemm_phase_init(int TM, int TN, int K, int lda, int ldb, AF a_of, BF b_of, INI ini, EPI epi, int bid, int nb, u16* sm) {
;     ...
;   for (int it = 0; have; it++) {
;     f32x16 acc[2][2];
;     ini(acc, tm, tn);
;     gemm_main(acc, a_of(tm), lda, b_of(tn), ldb, K, sm);
.LBB0_679:
	s_mov_b32 s12, s6
	v_mov_b32_e32 v2, v202
	s_mov_b32 s10, s8
	s_ashr_i32 s11, s8, 31
	s_ashr_i32 s13, s12, 31
	s_lshl_b64 s[6:7], s[10:11], 18
	s_lshl_b64 s[8:9], s[12:13], 18
	v_lshrrev_b32_e32 v3, 5, v2
	v_bfe_u32 v4, v2, 5, 1
	v_lshrrev_b32_e32 v5, 1, v2
	v_lshlrev_b32_e32 v6, 7, v2
	v_and_b32_e32 v7, 31, v2
	v_bfe_u32 v2, v2, 1, 3
	v_bitop3_b32 v3, v3, v2, 1 bitop3:0x6c
	s_add_u32 s6, s25, s6
	s_waitcnt vmcnt(32)
	v_lshlrev_b32_e32 v102, 4, v3
	v_bitop3_b32 v3, v4, v2, 2 bitop3:0x36
	s_addc_u32 s7, s26, s7
	v_and_or_b32 v5, v5, s29, v7
	v_lshlrev_b32_e32 v103, 4, v3
	v_bitop3_b32 v3, v4, v2, 4 bitop3:0x36
	v_bitop3_b32 v2, v4, v2, 6 bitop3:0x36
	s_add_u32 s8, s27, s8
	v_and_b32_e32 v66, 0x80, v6
	v_lshlrev_b32_e32 v68, 7, v5
	v_and_b32_e32 v69, 0x2f00, v6
	v_lshlrev_b32_e32 v104, 4, v3
	v_lshlrev_b32_e32 v105, 4, v2
	s_addc_u32 s9, s28, s9
	s_mov_b64 s[14:15], 0
	s_mov_b32 s13, 0
	s_mov_b32 s11, 0
	v_mov_b32_e32 v2, 0
	v_mov_b32_e32 v3, v67
	v_mov_b32_e32 v4, v67
	v_mov_b32_e32 v5, v67
	v_mov_b32_e32 v6, v67
	v_mov_b32_e32 v7, v67
	v_mov_b32_e32 v8, v67
	v_mov_b32_e32 v9, v67
	v_mov_b32_e32 v10, v67
	v_mov_b32_e32 v11, v67
	v_mov_b32_e32 v12, v67
	v_mov_b32_e32 v13, v67
	v_mov_b32_e32 v14, v67
	v_mov_b32_e32 v15, v67
	v_mov_b32_e32 v16, v67
	v_mov_b32_e32 v17, v67
	v_mov_b32_e32 v18, 0
	v_mov_b32_e32 v19, v67
	v_mov_b32_e32 v20, v67
	v_mov_b32_e32 v21, v67
	v_mov_b32_e32 v22, v67
	v_mov_b32_e32 v23, v67
	v_mov_b32_e32 v24, v67
	v_mov_b32_e32 v25, v67
	v_mov_b32_e32 v26, v67
	v_mov_b32_e32 v27, v67
	v_mov_b32_e32 v28, v67
	v_mov_b32_e32 v29, v67
	v_mov_b32_e32 v30, v67
	v_mov_b32_e32 v31, v67
	v_mov_b32_e32 v32, v67
	v_mov_b32_e32 v33, v67
	v_mov_b32_e32 v34, 0
	v_mov_b32_e32 v35, v67
	v_mov_b32_e32 v36, v67
	v_mov_b32_e32 v37, v67
	v_mov_b32_e32 v38, v67
	v_mov_b32_e32 v39, v67
	v_mov_b32_e32 v40, v67
	v_mov_b32_e32 v41, v67
	v_mov_b32_e32 v42, v67
	v_mov_b32_e32 v43, v67
	v_mov_b32_e32 v44, v67
	v_mov_b32_e32 v45, v67
	v_mov_b32_e32 v46, v67
	v_mov_b32_e32 v47, v67
	v_mov_b32_e32 v48, v67
	v_mov_b32_e32 v49, v67
	v_mov_b32_e32 v50, 0
	v_mov_b32_e32 v51, v67
	v_mov_b32_e32 v52, v67
	v_mov_b32_e32 v53, v67
	v_mov_b32_e32 v54, v67
	v_mov_b32_e32 v55, v67
	v_mov_b32_e32 v56, v67
	v_mov_b32_e32 v57, v67
	v_mov_b32_e32 v58, v67
	v_mov_b32_e32 v59, v67
	v_mov_b32_e32 v60, v67
	v_mov_b32_e32 v61, v67
	v_mov_b32_e32 v62, v67
	v_mov_b32_e32 v63, v67
	v_mov_b32_e32 v64, v67
	v_mov_b32_e32 v65, v67
	s_waitcnt vmcnt(32) lgkmcnt(0)
	s_barrier
	s_branch .LBB0_681

; #define MFMA32(a, b, c) __builtin_amdgcn_mfma_f32_32x32x16_bf16((a), (b), (c), 0, 0, 0)
; #define GAS __attribute__((address_space(1)))
; DI void gemm_stage(const u16* __restrict__ A, int lda, const u16* __restrict__ B, int ldb, int kt, char* sbuf) {
;     ...
;   for (int i = 0; i < 4; i++) {
;     const int blk = i * 4 + wave;
;     const int p = blk * 4 + pp;
;     const int row = 2 * p + (pos >> 3), c8 = (pos & 7) ^ (p & 7);
;     const u16* ga = A + (size_t)row * lda + kt * 64 + c8 * 8;
;     const u16* gb = B + (size_t)row * ldb + kt * 64 + c8 * 8;
;     __builtin_amdgcn_global_load_lds((const GAS void*)ga, (__attribute__((address_space(3))) void*)(sbuf + blk * 1024), 16, 0, 0);
;     __builtin_amdgcn_global_load_lds((const GAS void*)gb, (__attribute__((address_space(3))) void*)(sbuf + 16384 + blk * 1024), 16, 0, 0);
;   }
; DI void gemm_main(f32x16 (&acc)[2][2], const u16* __restrict__ A, int lda, const u16* __restrict__ B, int ldb, int K, u16* sm) {
;     ...
;   for (int kt = 0; kt < nk; kt++) {
;     if (kt + 1 < nk) gemm_stage(A, lda, B, ldb, kt + 1, sb + ((kt + 1) & 1) * GST_);
;     const char* st = sb + (kt & 1) * GST_;
; #pragma unroll
;     for (int ks = 0; ks < 4; ks++) {
;       const int ca = ((ks * 2 + hh) ^ xa) << 4, cb = ((ks * 2 + hh) ^ xb) << 4;
;       const bf16x8 fa0 = *(const bf16x8*)(st + baseA + ca);
;       const bf16x8 fa1 = *(const bf16x8*)(st + baseA + 4096 + ca);
;       const bf16x8 fb0 = *(const bf16x8*)(st + baseB + cb);
;       const bf16x8 fb1 = *(const bf16x8*)(st + baseB + 4096 + cb);
;       acc[0][0] = MFMA32(fa0, fb0, acc[0][0]); acc[0][1] = MFMA32(fa0, fb1, acc[0][1]);
;       acc[1][0] = MFMA32(fa1, fb0, acc[1][0]); acc[1][1] = MFMA32(fa1, fb1, acc[1][1]);
;     }
;     asm volatile("s_waitcnt vmcnt(0)" ::: "memory");
;     __syncthreads();
;   }
.Lkl0_top:
	s_cmp_lt_u32 s31, 15
	s_cbranch_scc0 .Lkl0_last
	v_add_u32_e32 v122, s11, v68
	v_add3_u32 v123, s11, v69, v66
	v_add_u32_e32 v114, v122, v102
	v_add_u32_e32 v118, v123, v102
	ds_read_b128 v[106:109], v114
	ds_read_b128 v[110:113], v118 offset:16384
	ds_read_b128 v[114:117], v114 offset:4096
	ds_read_b128 v[118:121], v118 offset:20480
	v_add_u32_e32 v248, v122, v103
	v_add_u32_e32 v252, v123, v103
	ds_read_b128 v[240:243], v248
	ds_read_b128 v[244:247], v252 offset:16384
	ds_read_b128 v[248:251], v248 offset:4096
	ds_read_b128 v[252:255], v252 offset:20480
	s_xor_b32 s13, s11, 0x8000
	s_add_i32 m0, s13, s33
	global_load_lds_dwordx4 v238, s[6:7]
	s_add_i32 m0, m0, 0x1000
	s_nop 0
	global_load_lds_dwordx4 v239, s[6:7]
	s_add_i32 m0, m0, 0x1000
	s_nop 0
	global_load_lds_dwordx4 v238, s[14:15]
	s_add_i32 m0, m0, 0x1000
	s_nop 0
	global_load_lds_dwordx4 v239, s[14:15]
	s_add_i32 m0, m0, 0x1000
	s_nop 0
	global_load_lds_dwordx4 v238, s[8:9]
	s_add_i32 m0, m0, 0x1000
	s_nop 0
	global_load_lds_dwordx4 v239, s[8:9]
	s_add_i32 m0, m0, 0x1000
	s_nop 0
	global_load_lds_dwordx4 v238, s[16:17]
	s_add_i32 m0, m0, 0x1000
	s_nop 0
	global_load_lds_dwordx4 v239, s[16:17]
	s_nop 0
	v_add_u32_e32 v238, 0x80, v238
	v_add_u32_e32 v239, 0x80, v239
	s_waitcnt lgkmcnt(4)
	v_mfma_f32_32x32x16_bf16 v[18:33], v[114:117], v[110:113], v[18:33]
	v_mfma_f32_32x32x16_bf16 v[2:17], v[114:117], v[118:121], v[2:17]
	v_mfma_f32_32x32x16_bf16 v[50:65], v[106:109], v[110:113], v[50:65]
	v_mfma_f32_32x32x16_bf16 v[34:49], v[106:109], v[118:121], v[34:49]
	v_add_u32_e32 v114, v122, v104
	v_add_u32_e32 v118, v123, v104
	ds_read_b128 v[106:109], v114
	ds_read_b128 v[110:113], v118 offset:16384
	ds_read_b128 v[114:117], v114 offset:4096
	ds_read_b128 v[118:121], v118 offset:20480
	s_waitcnt lgkmcnt(4)
	v_mfma_f32_32x32x16_bf16 v[18:33], v[248:251], v[244:247], v[18:33]
	v_mfma_f32_32x32x16_bf16 v[2:17], v[248:251], v[252:255], v[2:17]
	v_mfma_f32_32x32x16_bf16 v[50:65], v[240:243], v[244:247], v[50:65]
	v_mfma_f32_32x32x16_bf16 v[34:49], v[240:243], v[252:255], v[34:49]
	v_add_u32_e32 v248, v122, v105
	v_add_u32_e32 v252, v123, v105
	ds_read_b128 v[240:243], v248
	ds_read_b128 v[244:247], v252 offset:16384
	ds_read_b128 v[248:251], v248 offset:4096
	ds_read_b128 v[252:255], v252 offset:20480
	s_waitcnt lgkmcnt(4)
	v_mfma_f32_32x32x16_bf16 v[18:33], v[114:117], v[110:113], v[18:33]
	v_mfma_f32_32x32x16_bf16 v[2:17], v[114:117], v[118:121], v[2:17]
	v_mfma_f32_32x32x16_bf16 v[50:65], v[106:109], v[110:113], v[50:65]
	v_mfma_f32_32x32x16_bf16 v[34:49], v[106:109], v[118:121], v[34:49]
	s_add_i32 s31, s31, 1
	s_waitcnt vmcnt(0) lgkmcnt(0)
	s_barrier
	v_mfma_f32_32x32x16_bf16 v[50:65], v[240:243], v[244:247], v[50:65]
	v_mfma_f32_32x32x16_bf16 v[34:49], v[240:243], v[252:255], v[34:49]
	v_mfma_f32_32x32x16_bf16 v[18:33], v[248:251], v[244:247], v[18:33]
	v_mfma_f32_32x32x16_bf16 v[2:17], v[248:251], v[252:255], v[2:17]
	s_mov_b32 s11, s13
	s_branch .Lkl0_top

; #define MFMA32(a, b, c) __builtin_amdgcn_mfma_f32_32x32x16_bf16((a), (b), (c), 0, 0, 0)
; #define GAS __attribute__((address_space(1)))
; DI void gemm_stage(const u16* __restrict__ A, int lda, const u16* __restrict__ B, int ldb, int kt, char* sbuf) {
;     ...
;   for (int i = 0; i < 4; i++) {
;     const int blk = i * 4 + wave;
;     const int p = blk * 4 + pp;
;     const int row = 2 * p + (pos >> 3), c8 = (pos & 7) ^ (p & 7);
;     const u16* ga = A + (size_t)row * lda + kt * 64 + c8 * 8;
;     const u16* gb = B + (size_t)row * ldb + kt * 64 + c8 * 8;
;     __builtin_amdgcn_global_load_lds((const GAS void*)ga, (__attribute__((address_space(3))) void*)(sbuf + blk * 1024), 16, 0, 0);
;     __builtin_amdgcn_global_load_lds((const GAS void*)gb, (__attribute__((address_space(3))) void*)(sbuf + 16384 + blk * 1024), 16, 0, 0);
;   }
; DI void gemm_main(f32x16 (&acc)[2][2], const u16* __restrict__ A, int lda, const u16* __restrict__ B, int ldb, int K, u16* sm) {
;     ...
;   for (int kt = 0; kt < nk; kt++) {
;     if (kt + 1 < nk) gemm_stage(A, lda, B, ldb, kt + 1, sb + ((kt + 1) & 1) * GST_);
;     const char* st = sb + (kt & 1) * GST_;
; #pragma unroll
;     for (int ks = 0; ks < 4; ks++) {
;       const int ca = ((ks * 2 + hh) ^ xa) << 4, cb = ((ks * 2 + hh) ^ xb) << 4;
;       const bf16x8 fa0 = *(const bf16x8*)(st + baseA + ca);
;       const bf16x8 fa1 = *(const bf16x8*)(st + baseA + 4096 + ca);
;       const bf16x8 fb0 = *(const bf16x8*)(st + baseB + cb);
;       const bf16x8 fb1 = *(const bf16x8*)(st + baseB + 4096 + cb);
;       acc[0][0] = MFMA32(fa0, fb0, acc[0][0]); acc[0][1] = MFMA32(fa0, fb1, acc[0][1]);
;       acc[1][0] = MFMA32(fa1, fb0, acc[1][0]); acc[1][1] = MFMA32(fa1, fb1, acc[1][1]);
;     }
;     asm volatile("s_waitcnt vmcnt(0)" ::: "memory");
;     __syncthreads();
;   }
.Lkl1_top:
	s_cmp_lt_u32 s33, 15
	s_cbranch_scc0 .Lkl1_last
	v_add_u32_e32 v80, s7, v74
	v_add3_u32 v102, s7, v75, v66
	v_add_u32_e32 v94, v80, v76
	v_add_u32_e32 v98, v102, v76
	ds_read_b128 v[86:89], v94
	ds_read_b128 v[90:93], v98 offset:16384
	ds_read_b128 v[94:97], v94 offset:4096
	ds_read_b128 v[98:101], v98 offset:20480
	v_add_u32_e32 v248, v80, v77
	v_add_u32_e32 v252, v102, v77
	ds_read_b128 v[240:243], v248
	ds_read_b128 v[244:247], v252 offset:16384
	ds_read_b128 v[248:251], v248 offset:4096
	ds_read_b128 v[252:255], v252 offset:20480
	s_xor_b32 s15, s7, 0x8000
	s_add_i32 m0, s15, s36
	global_load_lds_dwordx4 v238, s[8:9]
	s_add_i32 m0, m0, 0x1000
	s_nop 0
	global_load_lds_dwordx4 v239, s[8:9]
	s_add_i32 m0, m0, 0x1000
	s_nop 0
	global_load_lds_dwordx4 v238, s[12:13]
	s_add_i32 m0, m0, 0x1000
	s_nop 0
	global_load_lds_dwordx4 v239, s[12:13]
	s_add_i32 m0, m0, 0x1000
	s_nop 0
	global_load_lds_dwordx4 v238, s[10:11]
	s_add_i32 m0, m0, 0x1000
	s_nop 0
	global_load_lds_dwordx4 v239, s[10:11]
	s_add_i32 m0, m0, 0x1000
	s_nop 0
	global_load_lds_dwordx4 v238, s[34:35]
	s_add_i32 m0, m0, 0x1000
	s_nop 0
	global_load_lds_dwordx4 v239, s[34:35]
	s_nop 0
	v_add_u32_e32 v238, 0x80, v238
	v_add_u32_e32 v239, 0x80, v239
	s_waitcnt lgkmcnt(4)
	v_mfma_f32_32x32x16_bf16 v[34:49], v[94:97], v[90:93], v[34:49]
	v_mfma_f32_32x32x16_bf16 v[50:65], v[86:89], v[90:93], v[50:65]
	v_mfma_f32_32x32x16_bf16 v[18:33], v[86:89], v[98:101], v[18:33]
	v_mfma_f32_32x32x16_bf16 v[2:17], v[94:97], v[98:101], v[2:17]
	v_add_u32_e32 v94, v80, v78
	v_add_u32_e32 v98, v102, v78
	ds_read_b128 v[86:89], v94
	ds_read_b128 v[90:93], v98 offset:16384
	ds_read_b128 v[94:97], v94 offset:4096
	ds_read_b128 v[98:101], v98 offset:20480
	s_waitcnt lgkmcnt(4)
	v_mfma_f32_32x32x16_bf16 v[34:49], v[248:251], v[244:247], v[34:49]
	v_mfma_f32_32x32x16_bf16 v[50:65], v[240:243], v[244:247], v[50:65]
	v_mfma_f32_32x32x16_bf16 v[18:33], v[240:243], v[252:255], v[18:33]
	v_mfma_f32_32x32x16_bf16 v[2:17], v[248:251], v[252:255], v[2:17]
	v_add_u32_e32 v248, v80, v79
	v_add_u32_e32 v252, v102, v79
	ds_read_b128 v[240:243], v248
	ds_read_b128 v[244:247], v252 offset:16384
	ds_read_b128 v[248:251], v248 offset:4096
	ds_read_b128 v[252:255], v252 offset:20480
	s_waitcnt lgkmcnt(4)
	v_mfma_f32_32x32x16_bf16 v[34:49], v[94:97], v[90:93], v[34:49]
	v_mfma_f32_32x32x16_bf16 v[50:65], v[86:89], v[90:93], v[50:65]
	v_mfma_f32_32x32x16_bf16 v[18:33], v[86:89], v[98:101], v[18:33]
	v_mfma_f32_32x32x16_bf16 v[2:17], v[94:97], v[98:101], v[2:17]
	s_add_i32 s33, s33, 1
	s_waitcnt vmcnt(0) lgkmcnt(0)
	s_barrier
	v_mfma_f32_32x32x16_bf16 v[50:65], v[240:243], v[244:247], v[50:65]
	v_mfma_f32_32x32x16_bf16 v[18:33], v[240:243], v[252:255], v[18:33]
	v_mfma_f32_32x32x16_bf16 v[34:49], v[248:251], v[244:247], v[34:49]
	v_mfma_f32_32x32x16_bf16 v[2:17], v[248:251], v[252:255], v[2:17]
	s_mov_b32 s7, s15
	s_branch .Lkl1_top

; #define MFMA32(a, b, c) __builtin_amdgcn_mfma_f32_32x32x16_bf16((a), (b), (c), 0, 0, 0)
; #define GAS __attribute__((address_space(1)))
; DI void gemm_stage(const u16* __restrict__ A, int lda, const u16* __restrict__ B, int ldb, int kt, char* sbuf) {
;     ...
;   for (int i = 0; i < 4; i++) {
;     const int blk = i * 4 + wave;
;     const int p = blk * 4 + pp;
;     const int row = 2 * p + (pos >> 3), c8 = (pos & 7) ^ (p & 7);
;     const u16* ga = A + (size_t)row * lda + kt * 64 + c8 * 8;
;     const u16* gb = B + (size_t)row * ldb + kt * 64 + c8 * 8;
;     __builtin_amdgcn_global_load_lds((const GAS void*)ga, (__attribute__((address_space(3))) void*)(sbuf + blk * 1024), 16, 0, 0);
;     __builtin_amdgcn_global_load_lds((const GAS void*)gb, (__attribute__((address_space(3))) void*)(sbuf + 16384 + blk * 1024), 16, 0, 0);
;   }
; DI void gemm_main(f32x16 (&acc)[2][2], const u16* __restrict__ A, int lda, const u16* __restrict__ B, int ldb, int K, u16* sm) {
;     ...
;   for (int kt = 0; kt < nk; kt++) {
;     if (kt + 1 < nk) gemm_stage(A, lda, B, ldb, kt + 1, sb + ((kt + 1) & 1) * GST_);
;     const char* st = sb + (kt & 1) * GST_;
; #pragma unroll
;     for (int ks = 0; ks < 4; ks++) {
;       const int ca = ((ks * 2 + hh) ^ xa) << 4, cb = ((ks * 2 + hh) ^ xb) << 4;
;       const bf16x8 fa0 = *(const bf16x8*)(st + baseA + ca);
;       const bf16x8 fa1 = *(const bf16x8*)(st + baseA + 4096 + ca);
;       const bf16x8 fb0 = *(const bf16x8*)(st + baseB + cb);
;       const bf16x8 fb1 = *(const bf16x8*)(st + baseB + 4096 + cb);
;       acc[0][0] = MFMA32(fa0, fb0, acc[0][0]); acc[0][1] = MFMA32(fa0, fb1, acc[0][1]);
;       acc[1][0] = MFMA32(fa1, fb0, acc[1][0]); acc[1][1] = MFMA32(fa1, fb1, acc[1][1]);
;     }
;     asm volatile("s_waitcnt vmcnt(0)" ::: "memory");
;     __syncthreads();
;   }
.Lkl2_top:
	s_cmp_lt_u32 s30, 3
	s_cbranch_scc0 .Lkl2_last
	v_add_u32_e32 v90, s15, v68
	v_add3_u32 v91, s15, v69, v66
	v_add_u32_e32 v82, v90, v70
	v_add_u32_e32 v86, v91, v70
	ds_read_b128 v[74:77], v82
	ds_read_b128 v[78:81], v86 offset:16384
	ds_read_b128 v[82:85], v82 offset:4096
	ds_read_b128 v[86:89], v86 offset:20480
	v_add_u32_e32 v248, v90, v71
	v_add_u32_e32 v252, v91, v71
	ds_read_b128 v[240:243], v248
	ds_read_b128 v[244:247], v252 offset:16384
	ds_read_b128 v[248:251], v248 offset:4096
	ds_read_b128 v[252:255], v252 offset:20480
	s_xor_b32 s17, s15, 0x8000
	s_add_i32 m0, s17, s31
	global_load_lds_dwordx4 v238, s[8:9]
	s_add_i32 m0, m0, 0x1000
	s_nop 0
	global_load_lds_dwordx4 v239, s[8:9]
	s_add_i32 m0, m0, 0x1000
	s_nop 0
	global_load_lds_dwordx4 v238, s[12:13]
	s_add_i32 m0, m0, 0x1000
	s_nop 0
	global_load_lds_dwordx4 v239, s[12:13]
	s_add_i32 m0, m0, 0x1000
	s_nop 0
	global_load_lds_dwordx4 v238, s[10:11]
	s_add_i32 m0, m0, 0x1000
	s_nop 0
	global_load_lds_dwordx4 v239, s[10:11]
	s_add_i32 m0, m0, 0x1000
	s_nop 0
	global_load_lds_dwordx4 v238, s[18:19]
	s_add_i32 m0, m0, 0x1000
	s_nop 0
	global_load_lds_dwordx4 v239, s[18:19]
	s_nop 0
	v_add_u32_e32 v238, 0x80, v238
	v_add_u32_e32 v239, 0x80, v239
	s_waitcnt lgkmcnt(4)
	v_mfma_f32_32x32x16_bf16 v[18:33], v[82:85], v[78:81], v[18:33]
	v_mfma_f32_32x32x16_bf16 v[2:17], v[82:85], v[86:89], v[2:17]
	v_mfma_f32_32x32x16_bf16 v[50:65], v[74:77], v[78:81], v[50:65]
	v_mfma_f32_32x32x16_bf16 v[34:49], v[74:77], v[86:89], v[34:49]
	v_add_u32_e32 v82, v90, v72
	v_add_u32_e32 v86, v91, v72
	ds_read_b128 v[74:77], v82
	ds_read_b128 v[78:81], v86 offset:16384
	ds_read_b128 v[82:85], v82 offset:4096
	ds_read_b128 v[86:89], v86 offset:20480
	s_waitcnt lgkmcnt(4)
	v_mfma_f32_32x32x16_bf16 v[18:33], v[248:251], v[244:247], v[18:33]
	v_mfma_f32_32x32x16_bf16 v[2:17], v[248:251], v[252:255], v[2:17]
	v_mfma_f32_32x32x16_bf16 v[50:65], v[240:243], v[244:247], v[50:65]
	v_mfma_f32_32x32x16_bf16 v[34:49], v[240:243], v[252:255], v[34:49]
	v_add_u32_e32 v248, v90, v73
	v_add_u32_e32 v252, v91, v73
	ds_read_b128 v[240:243], v248
	ds_read_b128 v[244:247], v252 offset:16384
	ds_read_b128 v[248:251], v248 offset:4096
	ds_read_b128 v[252:255], v252 offset:20480
	s_waitcnt lgkmcnt(4)
	v_mfma_f32_32x32x16_bf16 v[18:33], v[82:85], v[78:81], v[18:33]
	v_mfma_f32_32x32x16_bf16 v[2:17], v[82:85], v[86:89], v[2:17]
	v_mfma_f32_32x32x16_bf16 v[50:65], v[74:77], v[78:81], v[50:65]
	v_mfma_f32_32x32x16_bf16 v[34:49], v[74:77], v[86:89], v[34:49]
	s_add_i32 s30, s30, 1
	s_waitcnt vmcnt(0) lgkmcnt(0)
	s_barrier
	v_mfma_f32_32x32x16_bf16 v[50:65], v[240:243], v[244:247], v[50:65]
	v_mfma_f32_32x32x16_bf16 v[34:49], v[240:243], v[252:255], v[34:49]
	v_mfma_f32_32x32x16_bf16 v[18:33], v[248:251], v[244:247], v[18:33]
	v_mfma_f32_32x32x16_bf16 v[2:17], v[248:251], v[252:255], v[2:17]
	s_mov_b32 s15, s17
	s_branch .Lkl2_top

; #define MFMA32(a, b, c) __builtin_amdgcn_mfma_f32_32x32x16_bf16((a), (b), (c), 0, 0, 0)
; #define GAS __attribute__((address_space(1)))
; DI void gemm_stage(const u16* __restrict__ A, int lda, const u16* __restrict__ B, int ldb, int kt, char* sbuf) {
;     ...
;   for (int i = 0; i < 4; i++) {
;     const int blk = i * 4 + wave;
;     const int p = blk * 4 + pp;
;     const int row = 2 * p + (pos >> 3), c8 = (pos & 7) ^ (p & 7);
;     const u16* ga = A + (size_t)row * lda + kt * 64 + c8 * 8;
;     const u16* gb = B + (size_t)row * ldb + kt * 64 + c8 * 8;
;     __builtin_amdgcn_global_load_lds((const GAS void*)ga, (__attribute__((address_space(3))) void*)(sbuf + blk * 1024), 16, 0, 0);
;     __builtin_amdgcn_global_load_lds((const GAS void*)gb, (__attribute__((address_space(3))) void*)(sbuf + 16384 + blk * 1024), 16, 0, 0);
;   }
; DI void gemm_main(f32x16 (&acc)[2][2], const u16* __restrict__ A, int lda, const u16* __restrict__ B, int ldb, int K, u16* sm) {
;     ...
;   for (int kt = 0; kt < nk; kt++) {
;     if (kt + 1 < nk) gemm_stage(A, lda, B, ldb, kt + 1, sb + ((kt + 1) & 1) * GST_);
;     const char* st = sb + (kt & 1) * GST_;
; #pragma unroll
;     for (int ks = 0; ks < 4; ks++) {
;       const int ca = ((ks * 2 + hh) ^ xa) << 4, cb = ((ks * 2 + hh) ^ xb) << 4;
;       const bf16x8 fa0 = *(const bf16x8*)(st + baseA + ca);
;       const bf16x8 fa1 = *(const bf16x8*)(st + baseA + 4096 + ca);
;       const bf16x8 fb0 = *(const bf16x8*)(st + baseB + cb);
;       const bf16x8 fb1 = *(const bf16x8*)(st + baseB + 4096 + cb);
;       acc[0][0] = MFMA32(fa0, fb0, acc[0][0]); acc[0][1] = MFMA32(fa0, fb1, acc[0][1]);
;       acc[1][0] = MFMA32(fa1, fb0, acc[1][0]); acc[1][1] = MFMA32(fa1, fb1, acc[1][1]);
;     }
;     asm volatile("s_waitcnt vmcnt(0)" ::: "memory");
;     __syncthreads();
;   }
.Lkl3_top:
	s_cmp_lt_u32 s31, 15
	s_cbranch_scc0 .Lkl3_last
	v_add_u32_e32 v173, s29, v167
	v_add3_u32 v190, s29, v168, v71
	v_add_u32_e32 v182, v173, v169
	v_add_u32_e32 v186, v190, v169
	ds_read_b128 v[174:177], v182
	ds_read_b128 v[178:181], v186 offset:16384
	ds_read_b128 v[182:185], v182 offset:4096
	ds_read_b128 v[186:189], v186 offset:20480
	v_add_u32_e32 v248, v173, v170
	v_add_u32_e32 v252, v190, v170
	ds_read_b128 v[240:243], v248
	ds_read_b128 v[244:247], v252 offset:16384
	ds_read_b128 v[248:251], v248 offset:4096
	ds_read_b128 v[252:255], v252 offset:20480
	s_xor_b32 s30, s29, 0x8000
	s_add_i32 m0, s30, s33
	global_load_lds_dwordx4 v238, s[10:11]
	s_add_i32 m0, m0, 0x1000
	s_nop 0
	global_load_lds_dwordx4 v239, s[10:11]
	s_add_i32 m0, m0, 0x1000
	s_nop 0
	global_load_lds_dwordx4 v238, s[14:15]
	s_add_i32 m0, m0, 0x1000
	s_nop 0
	global_load_lds_dwordx4 v239, s[14:15]
	s_add_i32 m0, m0, 0x1000
	s_nop 0
	global_load_lds_dwordx4 v238, s[12:13]
	s_add_i32 m0, m0, 0x1000
	s_nop 0
	global_load_lds_dwordx4 v239, s[12:13]
	s_add_i32 m0, m0, 0x1000
	s_nop 0
	global_load_lds_dwordx4 v238, s[16:17]
	s_add_i32 m0, m0, 0x1000
	s_nop 0
	global_load_lds_dwordx4 v239, s[16:17]
	s_nop 0
	v_add_u32_e32 v238, 0x80, v238
	v_add_u32_e32 v239, 0x80, v239
	s_waitcnt lgkmcnt(4)
	v_mfma_f32_32x32x16_bf16 v[18:33], v[182:185], v[178:181], v[18:33]
	v_mfma_f32_32x32x16_bf16 v[34:49], v[182:185], v[186:189], v[34:49]
	v_mfma_f32_32x32x16_bf16 v[2:17], v[174:177], v[178:181], v[2:17]
	v_mfma_f32_32x32x16_bf16 v[50:65], v[174:177], v[186:189], v[50:65]
	v_add_u32_e32 v182, v173, v171
	v_add_u32_e32 v186, v190, v171
	ds_read_b128 v[174:177], v182
	ds_read_b128 v[178:181], v186 offset:16384
	ds_read_b128 v[182:185], v182 offset:4096
	ds_read_b128 v[186:189], v186 offset:20480
	s_waitcnt lgkmcnt(4)
	v_mfma_f32_32x32x16_bf16 v[18:33], v[248:251], v[244:247], v[18:33]
	v_mfma_f32_32x32x16_bf16 v[34:49], v[248:251], v[252:255], v[34:49]
	v_mfma_f32_32x32x16_bf16 v[2:17], v[240:243], v[244:247], v[2:17]
	v_mfma_f32_32x32x16_bf16 v[50:65], v[240:243], v[252:255], v[50:65]
	v_add_u32_e32 v248, v173, v172
	v_add_u32_e32 v252, v190, v172
	ds_read_b128 v[240:243], v248
	ds_read_b128 v[244:247], v252 offset:16384
	ds_read_b128 v[248:251], v248 offset:4096
	ds_read_b128 v[252:255], v252 offset:20480
	s_waitcnt lgkmcnt(4)
	v_mfma_f32_32x32x16_bf16 v[18:33], v[182:185], v[178:181], v[18:33]
	v_mfma_f32_32x32x16_bf16 v[34:49], v[182:185], v[186:189], v[34:49]
	v_mfma_f32_32x32x16_bf16 v[2:17], v[174:177], v[178:181], v[2:17]
	v_mfma_f32_32x32x16_bf16 v[50:65], v[174:177], v[186:189], v[50:65]
	s_add_i32 s31, s31, 1
	s_waitcnt vmcnt(0) lgkmcnt(0)
	s_barrier
	v_mfma_f32_32x32x16_bf16 v[2:17], v[240:243], v[244:247], v[2:17]
	v_mfma_f32_32x32x16_bf16 v[50:65], v[240:243], v[252:255], v[50:65]
	v_mfma_f32_32x32x16_bf16 v[18:33], v[248:251], v[244:247], v[18:33]
	v_mfma_f32_32x32x16_bf16 v[34:49], v[248:251], v[252:255], v[34:49]
	s_mov_b32 s29, s30
	s_branch .Lkl3_top

; DI int tidx() { int t = threadIdx.x; asm volatile("" : "+v"(t)); return t; }
; #define GAS __attribute__((address_space(1)))
; DI void gemm_stage(const u16* __restrict__ A, int lda, const u16* __restrict__ B, int ldb, int kt, char* sbuf) {
;   const int tid = tidx(), lane = tid & 63, wave = __builtin_amdgcn_readfirstlane(tid >> 6);
;   const int pp = lane >> 4, pos = lane & 15;
; #pragma unroll
;   for (int i = 0; i < 4; i++) {
;     const int blk = i * 4 + wave;
;     const int p = blk * 4 + pp;
;     const int row = 2 * p + (pos >> 3), c8 = (pos & 7) ^ (p & 7);
;     const u16* ga = A + (size_t)row * lda + kt * 64 + c8 * 8;
;     const u16* gb = B + (size_t)row * ldb + kt * 64 + c8 * 8;
;     __builtin_amdgcn_global_load_lds((const GAS void*)ga, (__attribute__((address_space(3))) void*)(sbuf + blk * 1024), 16, 0, 0);
;     __builtin_amdgcn_global_load_lds((const GAS void*)gb, (__attribute__((address_space(3))) void*)(sbuf + 16384 + blk * 1024), 16, 0, 0);
;   }
; }
; template <class AF, class BF, class INI, class EPI>
; DI void gemm_phase_init(int TM, int TN, int K, int lda, int ldb, AF a_of, BF b_of, INI ini, EPI epi, int bid, int nb, u16* sm) {
;   int tm, tn;
;   bool have = tile_at(0, bid, nb, TM, TN, tm, tn);
;   __syncthreads();
;   if (have) gemm_stage(a_of(tm), lda, b_of(tn), ldb, 0, (char*)sm);
.LBB0_4573:
	v_readlane_b32 s12, v237, 0
	v_readlane_b32 s13, v237, 1
	s_add_u32 s3, s12, s4
	s_addc_u32 s20, s13, s5
	s_add_u32 s21, s3, 0x558d140
	s_addc_u32 s22, s20, 0
	s_andn2_b64 vcc, exec, s[6:7]
	s_waitcnt vmcnt(0) lgkmcnt(0)
	s_barrier
	s_cbranch_vccnz .LBB0_4592
	s_add_u32 s6, s3, 0x1158d140
	s_addc_u32 s7, s20, 0
	s_add_u32 s23, s3, 0x2100000
	s_addc_u32 s24, s20, 0
	s_ashr_i32 s11, s10, 31
	s_lshl_b64 s[12:13], s[10:11], 18
	s_add_u32 s12, s21, s12
	s_addc_u32 s13, s22, s13
	s_ashr_i32 s9, s8, 31
	s_lshl_b64 s[14:15], s[8:9], 18
	v_mov_b32_e32 v1, v202
	s_add_u32 s14, s23, s14
	s_addc_u32 s15, s24, s15
	v_readfirstlane_b32 s9, v1
	s_ashr_i32 s9, s9, 6
	v_bfe_u32 v8, v1, 4, 2
	s_lshl_b32 s11, s9, 2
	v_bfe_u32 v9, v1, 3, 1
	v_or_b32_e32 v4, s11, v8
	v_lshl_or_b32 v4, v4, 1, v9
	v_bitop3_b32 v10, s11, v1, v8 bitop3:0x36
	v_ashrrev_i32_e32 v5, 31, v4
	v_lshlrev_b64 v[4:5], 11, v[4:5]
	v_lshlrev_b32_e32 v10, 4, v10
	s_lshl_b32 s11, s9, 10
	v_lshl_add_u64 v[6:7], s[12:13], 0, v[4:5]
	v_and_b32_e32 v66, 0x70, v10
	v_mov_b32_e32 v67, 0
	s_add_i32 s11, s11, 0
	v_lshl_add_u64 v[6:7], v[6:7], 0, v[66:67]
	s_mov_b32 m0, s11
	v_lshl_add_u64 v[4:5], s[14:15], 0, v[4:5]
	global_load_lds_dwordx4 v[6:7], off
	s_add_i32 m0, s11, 0x4000
	s_add_i32 s11, s9, 4
	v_lshl_add_u64 v[4:5], v[4:5], 0, v[66:67]
	s_lshl_b32 s16, s11, 2
	global_load_lds_dwordx4 v[4:5], off
	v_or_b32_e32 v4, s16, v8
	v_lshl_or_b32 v4, v4, 1, v9
	v_bitop3_b32 v10, s16, v1, v8 bitop3:0x36
	v_ashrrev_i32_e32 v5, 31, v4
	v_lshlrev_b64 v[4:5], 11, v[4:5]
	v_lshlrev_b32_e32 v10, 4, v10
	s_lshl_b32 s11, s11, 10
	v_lshl_add_u64 v[6:7], s[12:13], 0, v[4:5]
	v_and_b32_e32 v66, 0x70, v10
	s_add_i32 s11, s11, 0
	v_lshl_add_u64 v[6:7], v[6:7], 0, v[66:67]
	s_mov_b32 m0, s11
	v_lshl_add_u64 v[4:5], s[14:15], 0, v[4:5]
	global_load_lds_dwordx4 v[6:7], off
	s_add_i32 m0, s11, 0x4000
	s_add_i32 s11, s9, 8
	v_lshl_add_u64 v[4:5], v[4:5], 0, v[66:67]
	s_lshl_b32 s16, s11, 2
	global_load_lds_dwordx4 v[4:5], off
	v_or_b32_e32 v4, s16, v8
	v_lshl_or_b32 v4, v4, 1, v9
	v_bitop3_b32 v10, s16, v1, v8 bitop3:0x36
	v_ashrrev_i32_e32 v5, 31, v4
	v_lshlrev_b64 v[4:5], 11, v[4:5]
	v_lshlrev_b32_e32 v10, 4, v10
	s_lshl_b32 s11, s11, 10
	v_lshl_add_u64 v[6:7], s[12:13], 0, v[4:5]
	v_and_b32_e32 v66, 0x70, v10
	s_add_i32 s11, s11, 0
	v_lshl_add_u64 v[6:7], v[6:7], 0, v[66:67]
	v_lshl_add_u64 v[4:5], s[14:15], 0, v[4:5]
	s_mov_b32 m0, s11
	s_add_i32 s9, s9, 12
	v_lshl_add_u64 v[4:5], v[4:5], 0, v[66:67]
	global_load_lds_dwordx4 v[6:7], off
	s_add_i32 m0, s11, 0x4000
	s_lshl_b32 s11, s9, 2
	global_load_lds_dwordx4 v[4:5], off
	v_or_b32_e32 v4, s11, v8
	v_lshl_or_b32 v4, v4, 1, v9
	v_bitop3_b32 v1, s11, v1, v8 bitop3:0x36
	v_ashrrev_i32_e32 v5, 31, v4
	v_lshlrev_b64 v[4:5], 11, v[4:5]
	v_lshlrev_b32_e32 v1, 4, v1
	s_lshl_b32 s9, s9, 10
	v_lshl_add_u64 v[6:7], s[12:13], 0, v[4:5]
	v_and_b32_e32 v66, 0x70, v1
	s_add_i32 s9, s9, 0
	v_lshl_add_u64 v[6:7], v[6:7], 0, v[66:67]
	v_lshl_add_u64 v[4:5], s[14:15], 0, v[4:5]
	s_mov_b32 m0, s9
	v_lshl_add_u64 v[4:5], v[4:5], 0, v[66:67]
	global_load_lds_dwordx4 v[6:7], off
	s_add_i32 m0, s9, 0x4000
	v_lshrrev_b32_e32 v1, 1, v3
	global_load_lds_dwordx4 v[4:5], off
	v_and_b32_e32 v1, 32, v1
	s_lshl_b32 s9, s2, 6
	v_and_or_b32 v1, v2, 31, v1
	v_lshrrev_b32_e32 v2, 3, v2
	s_ashr_i32 s26, s2, 3
	s_ashr_i32 s27, s94, 3
	s_and_b32 s28, s9, 0x1c0
	v_ashrrev_i32_e32 v3, 1, v3
	v_and_b32_e32 v2, 4, v2
	s_movk_i32 s9, 0xffc0
	v_readlane_b32 s12, v237, 0
	v_and_or_b32 v70, v3, s9, v2
	v_readlane_b32 s13, v237, 1
	s_add_u32 s9, s12, s4
	s_addc_u32 s11, s13, s5
	s_add_u32 s29, s9, 0x558d1c0
	s_addc_u32 s30, s11, 0
	s_add_u32 s31, s9, 0x2100080
	s_mov_b32 s25, 0
	v_or_b32_e32 v71, 1, v70
	v_or_b32_e32 v72, 2, v70
	v_or_b32_e32 v73, 3, v70
	v_or_b32_e32 v74, 8, v70
	v_or_b32_e32 v75, 9, v70
	v_or_b32_e32 v76, 10, v70
	v_or_b32_e32 v77, 11, v70
	v_or_b32_e32 v78, 16, v70
	v_or_b32_e32 v79, 17, v70
	v_or_b32_e32 v80, 18, v70
	v_or_b32_e32 v81, 19, v70
	v_or_b32_e32 v82, 24, v70
	v_or_b32_e32 v83, 25, v70
	v_or_b32_e32 v84, 26, v70
	v_or_b32_e32 v85, 27, v70
	v_or_b32_e32 v86, 32, v70
	v_or_b32_e32 v87, 33, v70
	v_or_b32_e32 v88, 34, v70
	v_or_b32_e32 v89, 35, v70
	v_or_b32_e32 v90, 40, v70
	v_or_b32_e32 v91, 41, v70
	v_or_b32_e32 v92, 42, v70
	v_or_b32_e32 v93, 43, v70
	v_or_b32_e32 v94, 48, v70
	v_or_b32_e32 v95, 49, v70
	v_or_b32_e32 v96, 50, v70
	v_or_b32_e32 v97, 51, v70
	v_or_b32_e32 v98, 56, v70
	v_or_b32_e32 v99, 57, v70
	v_or_b32_e32 v100, 58, v70
	v_or_b32_e32 v101, 59, v70
	s_addc_u32 s33, s11, 0
	s_mov_b32 s34, 0x1ffffc0
	s_movk_i32 s35, 0x1600
	s_waitcnt vmcnt(0)
	s_branch .LBB0_4576

; DI int tidx() { int t = threadIdx.x; asm volatile("" : "+v"(t)); return t; }
; DI void gemm_main(f32x16 (&acc)[2][2], const u16* __restrict__ A, int lda, const u16* __restrict__ B, int ldb, int K, u16* sm) {
;   const int tid = tidx(), lane = tid & 63, wave = tid >> 6;
;   const int wm = wave >> 1, wn = wave & 1, r = lane & 31, hh = lane >> 5;
;   char* sb = (char*)sm;
;   const int rowa = wm * 64 + r, rowb = wn * 64 + r;
;   const int baseA = (rowa >> 1) * 256 + ((rowa & 1) << 7), xa = (rowa >> 1) & 7;
;   const int baseB = 16384 + (rowb >> 1) * 256 + ((rowb & 1) << 7), xb = (rowb >> 1) & 7;
;   const int nk = K >> 6;
;   asm volatile("s_waitcnt vmcnt(0)" ::: "memory");
;   __syncthreads();
; template <class AF, class BF, class INI, class EPI>
; DI void gemm_phase_init(int TM, int TN, int K, int lda, int ldb, AF a_of, BF b_of, INI ini, EPI epi, int bid, int nb, u16* sm) {
;     ...
;   for (int it = 0; have; it++) {
;     f32x16 acc[2][2];
;     ini(acc, tm, tn);
;     gemm_main(acc, a_of(tm), lda, b_of(tn), ldb, K, sm);
.LBB0_4576:
	s_mov_b32 s14, s8
	v_mov_b32_e32 v2, v202
	s_mov_b32 s12, s10
	s_ashr_i32 s13, s10, 31
	s_ashr_i32 s15, s14, 31
	s_lshl_b64 s[8:9], s[12:13], 18
	s_lshl_b64 s[10:11], s[14:15], 18
	v_lshrrev_b32_e32 v3, 5, v2
	v_bfe_u32 v4, v2, 5, 1
	v_lshrrev_b32_e32 v5, 1, v2
	v_lshlrev_b32_e32 v6, 7, v2
	v_and_b32_e32 v7, 31, v2
	v_bfe_u32 v2, v2, 1, 3
	v_bitop3_b32 v3, v3, v2, 1 bitop3:0x6c
	s_add_u32 s8, s29, s8
	s_waitcnt vmcnt(32)
	v_lshlrev_b32_e32 v102, 4, v3
	v_bitop3_b32 v3, v4, v2, 2 bitop3:0x36
	s_addc_u32 s9, s30, s9
	v_and_or_b32 v5, v5, s34, v7
	v_lshlrev_b32_e32 v103, 4, v3
	v_bitop3_b32 v3, v4, v2, 4 bitop3:0x36
	v_bitop3_b32 v2, v4, v2, 6 bitop3:0x36
	s_add_u32 s10, s31, s10
	v_and_b32_e32 v66, 0x80, v6
	v_lshlrev_b32_e32 v68, 7, v5
	v_and_b32_e32 v69, 0x2f00, v6
	v_lshlrev_b32_e32 v104, 4, v3
	v_lshlrev_b32_e32 v105, 4, v2
	s_addc_u32 s11, s33, s11
	s_mov_b64 s[16:17], 0
	s_mov_b32 s15, 0
	s_mov_b32 s13, 0
	v_mov_b32_e32 v2, 0
	v_mov_b32_e32 v3, v67
	v_mov_b32_e32 v4, v67
	v_mov_b32_e32 v5, v67
	v_mov_b32_e32 v6, v67
	v_mov_b32_e32 v7, v67
	v_mov_b32_e32 v8, v67
	v_mov_b32_e32 v9, v67
	v_mov_b32_e32 v10, v67
	v_mov_b32_e32 v11, v67
	v_mov_b32_e32 v12, v67
	v_mov_b32_e32 v13, v67
	v_mov_b32_e32 v14, v67
	v_mov_b32_e32 v15, v67
	v_mov_b32_e32 v16, v67
	v_mov_b32_e32 v17, v67
	v_mov_b32_e32 v18, 0
	v_mov_b32_e32 v19, v67
	v_mov_b32_e32 v20, v67
	v_mov_b32_e32 v21, v67
	v_mov_b32_e32 v22, v67
	v_mov_b32_e32 v23, v67
	v_mov_b32_e32 v24, v67
	v_mov_b32_e32 v25, v67
	v_mov_b32_e32 v26, v67
	v_mov_b32_e32 v27, v67
	v_mov_b32_e32 v28, v67
	v_mov_b32_e32 v29, v67
	v_mov_b32_e32 v30, v67
	v_mov_b32_e32 v31, v67
	v_mov_b32_e32 v32, v67
	v_mov_b32_e32 v33, v67
	v_mov_b32_e32 v34, 0
	v_mov_b32_e32 v35, v67
	v_mov_b32_e32 v36, v67
	v_mov_b32_e32 v37, v67
	v_mov_b32_e32 v38, v67
	v_mov_b32_e32 v39, v67
	v_mov_b32_e32 v40, v67
	v_mov_b32_e32 v41, v67
	v_mov_b32_e32 v42, v67
	v_mov_b32_e32 v43, v67
	v_mov_b32_e32 v44, v67
	v_mov_b32_e32 v45, v67
	v_mov_b32_e32 v46, v67
	v_mov_b32_e32 v47, v67
	v_mov_b32_e32 v48, v67
	v_mov_b32_e32 v49, v67
	v_mov_b32_e32 v50, 0
	v_mov_b32_e32 v51, v67
	v_mov_b32_e32 v52, v67
	v_mov_b32_e32 v53, v67
	v_mov_b32_e32 v54, v67
	v_mov_b32_e32 v55, v67
	v_mov_b32_e32 v56, v67
	v_mov_b32_e32 v57, v67
	v_mov_b32_e32 v58, v67
	v_mov_b32_e32 v59, v67
	v_mov_b32_e32 v60, v67
	v_mov_b32_e32 v61, v67
	v_mov_b32_e32 v62, v67
	v_mov_b32_e32 v63, v67
	v_mov_b32_e32 v64, v67
	v_mov_b32_e32 v65, v67
	s_waitcnt vmcnt(32) lgkmcnt(0)
	s_barrier
	s_branch .LBB0_4578

; #define MFMA32(a, b, c) __builtin_amdgcn_mfma_f32_32x32x16_bf16((a), (b), (c), 0, 0, 0)
; #define GAS __attribute__((address_space(1)))
; DI void gemm_stage(const u16* __restrict__ A, int lda, const u16* __restrict__ B, int ldb, int kt, char* sbuf) {
;     ...
;   for (int i = 0; i < 4; i++) {
;     const int blk = i * 4 + wave;
;     const int p = blk * 4 + pp;
;     const int row = 2 * p + (pos >> 3), c8 = (pos & 7) ^ (p & 7);
;     const u16* ga = A + (size_t)row * lda + kt * 64 + c8 * 8;
;     const u16* gb = B + (size_t)row * ldb + kt * 64 + c8 * 8;
;     __builtin_amdgcn_global_load_lds((const GAS void*)ga, (__attribute__((address_space(3))) void*)(sbuf + blk * 1024), 16, 0, 0);
;     __builtin_amdgcn_global_load_lds((const GAS void*)gb, (__attribute__((address_space(3))) void*)(sbuf + 16384 + blk * 1024), 16, 0, 0);
;   }
; DI void gemm_main(f32x16 (&acc)[2][2], const u16* __restrict__ A, int lda, const u16* __restrict__ B, int ldb, int K, u16* sm) {
;     ...
;   for (int kt = 0; kt < nk; kt++) {
;     if (kt + 1 < nk) gemm_stage(A, lda, B, ldb, kt + 1, sb + ((kt + 1) & 1) * GST_);
;     const char* st = sb + (kt & 1) * GST_;
; #pragma unroll
;     for (int ks = 0; ks < 4; ks++) {
;       const int ca = ((ks * 2 + hh) ^ xa) << 4, cb = ((ks * 2 + hh) ^ xb) << 4;
;       const bf16x8 fa0 = *(const bf16x8*)(st + baseA + ca);
;       const bf16x8 fa1 = *(const bf16x8*)(st + baseA + 4096 + ca);
;       const bf16x8 fb0 = *(const bf16x8*)(st + baseB + cb);
;       const bf16x8 fb1 = *(const bf16x8*)(st + baseB + 4096 + cb);
;       acc[0][0] = MFMA32(fa0, fb0, acc[0][0]); acc[0][1] = MFMA32(fa0, fb1, acc[0][1]);
;       acc[1][0] = MFMA32(fa1, fb0, acc[1][0]); acc[1][1] = MFMA32(fa1, fb1, acc[1][1]);
;     }
;     asm volatile("s_waitcnt vmcnt(0)" ::: "memory");
;     __syncthreads();
;   }
.Lkl4_top:
	s_cmp_lt_u32 s36, 15
	s_cbranch_scc0 .Lkl4_last
	v_add_u32_e32 v122, s13, v68
	v_add3_u32 v123, s13, v69, v66
	v_add_u32_e32 v114, v122, v102
	v_add_u32_e32 v118, v123, v102
	ds_read_b128 v[106:109], v114
	ds_read_b128 v[110:113], v118 offset:16384
	ds_read_b128 v[114:117], v114 offset:4096
	ds_read_b128 v[118:121], v118 offset:20480
	v_add_u32_e32 v248, v122, v103
	v_add_u32_e32 v252, v123, v103
	ds_read_b128 v[240:243], v248
	ds_read_b128 v[244:247], v252 offset:16384
	ds_read_b128 v[248:251], v248 offset:4096
	ds_read_b128 v[252:255], v252 offset:20480
	s_xor_b32 s15, s13, 0x8000
	s_add_i32 m0, s15, s37
	global_load_lds_dwordx4 v238, s[8:9]
	s_add_i32 m0, m0, 0x1000
	s_nop 0
	global_load_lds_dwordx4 v239, s[8:9]
	s_add_i32 m0, m0, 0x1000
	s_nop 0
	global_load_lds_dwordx4 v238, s[16:17]
	s_add_i32 m0, m0, 0x1000
	s_nop 0
	global_load_lds_dwordx4 v239, s[16:17]
	s_add_i32 m0, m0, 0x1000
	s_nop 0
	global_load_lds_dwordx4 v238, s[10:11]
	s_add_i32 m0, m0, 0x1000
	s_nop 0
	global_load_lds_dwordx4 v239, s[10:11]
	s_add_i32 m0, m0, 0x1000
	s_nop 0
	global_load_lds_dwordx4 v238, s[18:19]
	s_add_i32 m0, m0, 0x1000
	s_nop 0
	global_load_lds_dwordx4 v239, s[18:19]
	s_nop 0
	v_add_u32_e32 v238, 0x80, v238
	v_add_u32_e32 v239, 0x80, v239
	s_waitcnt lgkmcnt(4)
	v_mfma_f32_32x32x16_bf16 v[18:33], v[114:117], v[110:113], v[18:33]
	v_mfma_f32_32x32x16_bf16 v[2:17], v[114:117], v[118:121], v[2:17]
	v_mfma_f32_32x32x16_bf16 v[50:65], v[106:109], v[110:113], v[50:65]
	v_mfma_f32_32x32x16_bf16 v[34:49], v[106:109], v[118:121], v[34:49]
	v_add_u32_e32 v114, v122, v104
	v_add_u32_e32 v118, v123, v104
	ds_read_b128 v[106:109], v114
	ds_read_b128 v[110:113], v118 offset:16384
	ds_read_b128 v[114:117], v114 offset:4096
	ds_read_b128 v[118:121], v118 offset:20480
	s_waitcnt lgkmcnt(4)
	v_mfma_f32_32x32x16_bf16 v[18:33], v[248:251], v[244:247], v[18:33]
	v_mfma_f32_32x32x16_bf16 v[2:17], v[248:251], v[252:255], v[2:17]
	v_mfma_f32_32x32x16_bf16 v[50:65], v[240:243], v[244:247], v[50:65]
	v_mfma_f32_32x32x16_bf16 v[34:49], v[240:243], v[252:255], v[34:49]
	v_add_u32_e32 v248, v122, v105
	v_add_u32_e32 v252, v123, v105
	ds_read_b128 v[240:243], v248
	ds_read_b128 v[244:247], v252 offset:16384
	ds_read_b128 v[248:251], v248 offset:4096
	ds_read_b128 v[252:255], v252 offset:20480
	s_waitcnt lgkmcnt(4)
	v_mfma_f32_32x32x16_bf16 v[18:33], v[114:117], v[110:113], v[18:33]
	v_mfma_f32_32x32x16_bf16 v[2:17], v[114:117], v[118:121], v[2:17]
	v_mfma_f32_32x32x16_bf16 v[50:65], v[106:109], v[110:113], v[50:65]
	v_mfma_f32_32x32x16_bf16 v[34:49], v[106:109], v[118:121], v[34:49]
	s_add_i32 s36, s36, 1
	s_waitcnt vmcnt(0) lgkmcnt(0)
	s_barrier
	v_mfma_f32_32x32x16_bf16 v[50:65], v[240:243], v[244:247], v[50:65]
	v_mfma_f32_32x32x16_bf16 v[34:49], v[240:243], v[252:255], v[34:49]
	v_mfma_f32_32x32x16_bf16 v[18:33], v[248:251], v[244:247], v[18:33]
	v_mfma_f32_32x32x16_bf16 v[2:17], v[248:251], v[252:255], v[2:17]
	s_mov_b32 s13, s15
	s_branch .Lkl4_top

; #define MFMA32(a, b, c) __builtin_amdgcn_mfma_f32_32x32x16_bf16((a), (b), (c), 0, 0, 0)
; #define GAS __attribute__((address_space(1)))
; DI void gemm_stage(const u16* __restrict__ A, int lda, const u16* __restrict__ B, int ldb, int kt, char* sbuf) {
;     ...
;   for (int i = 0; i < 4; i++) {
;     const int blk = i * 4 + wave;
;     const int p = blk * 4 + pp;
;     const int row = 2 * p + (pos >> 3), c8 = (pos & 7) ^ (p & 7);
;     const u16* ga = A + (size_t)row * lda + kt * 64 + c8 * 8;
;     const u16* gb = B + (size_t)row * ldb + kt * 64 + c8 * 8;
;     __builtin_amdgcn_global_load_lds((const GAS void*)ga, (__attribute__((address_space(3))) void*)(sbuf + blk * 1024), 16, 0, 0);
;     __builtin_amdgcn_global_load_lds((const GAS void*)gb, (__attribute__((address_space(3))) void*)(sbuf + 16384 + blk * 1024), 16, 0, 0);
;   }
; DI void gemm_main(f32x16 (&acc)[2][2], const u16* __restrict__ A, int lda, const u16* __restrict__ B, int ldb, int K, u16* sm) {
;     ...
;   for (int kt = 0; kt < nk; kt++) {
;     if (kt + 1 < nk) gemm_stage(A, lda, B, ldb, kt + 1, sb + ((kt + 1) & 1) * GST_);
;     const char* st = sb + (kt & 1) * GST_;
; #pragma unroll
;     for (int ks = 0; ks < 4; ks++) {
;       const int ca = ((ks * 2 + hh) ^ xa) << 4, cb = ((ks * 2 + hh) ^ xb) << 4;
;       const bf16x8 fa0 = *(const bf16x8*)(st + baseA + ca);
;       const bf16x8 fa1 = *(const bf16x8*)(st + baseA + 4096 + ca);
;       const bf16x8 fb0 = *(const bf16x8*)(st + baseB + cb);
;       const bf16x8 fb1 = *(const bf16x8*)(st + baseB + 4096 + cb);
;       acc[0][0] = MFMA32(fa0, fb0, acc[0][0]); acc[0][1] = MFMA32(fa0, fb1, acc[0][1]);
;       acc[1][0] = MFMA32(fa1, fb0, acc[1][0]); acc[1][1] = MFMA32(fa1, fb1, acc[1][1]);
;     }
;     asm volatile("s_waitcnt vmcnt(0)" ::: "memory");
;     __syncthreads();
;   }
.Lkl5_top:
	s_cmp_lt_u32 s35, 15
	s_cbranch_scc0 .Lkl5_last
	v_add_u32_e32 v111, s15, v74
	v_add3_u32 v128, s15, v75, v70
	v_add_u32_e32 v120, v111, v76
	v_add_u32_e32 v124, v128, v76
	ds_read_b128 v[112:115], v120
	ds_read_b128 v[116:119], v124 offset:16384
	ds_read_b128 v[120:123], v120 offset:4096
	ds_read_b128 v[124:127], v124 offset:20480
	v_add_u32_e32 v248, v111, v77
	v_add_u32_e32 v252, v128, v77
	ds_read_b128 v[240:243], v248
	ds_read_b128 v[244:247], v252 offset:16384
	ds_read_b128 v[248:251], v248 offset:4096
	ds_read_b128 v[252:255], v252 offset:20480
	s_xor_b32 s17, s15, 0x8000
	s_add_i32 m0, s17, s36
	global_load_lds_dwordx4 v238, s[8:9]
	s_add_i32 m0, m0, 0x1000
	s_nop 0
	global_load_lds_dwordx4 v239, s[8:9]
	s_add_i32 m0, m0, 0x1000
	s_nop 0
	global_load_lds_dwordx4 v238, s[12:13]
	s_add_i32 m0, m0, 0x1000
	s_nop 0
	global_load_lds_dwordx4 v239, s[12:13]
	s_add_i32 m0, m0, 0x1000
	s_nop 0
	global_load_lds_dwordx4 v238, s[10:11]
	s_add_i32 m0, m0, 0x1000
	s_nop 0
	global_load_lds_dwordx4 v239, s[10:11]
	s_add_i32 m0, m0, 0x1000
	s_nop 0
	global_load_lds_dwordx4 v238, s[18:19]
	s_add_i32 m0, m0, 0x1000
	s_nop 0
	global_load_lds_dwordx4 v239, s[18:19]
	s_nop 0
	v_add_u32_e32 v238, 0x80, v238
	v_add_u32_e32 v239, 0x80, v239
	s_waitcnt lgkmcnt(4)
	v_mfma_f32_32x32x16_bf16 v[18:33], v[120:123], v[116:119], v[18:33]
	v_mfma_f32_32x32x16_bf16 v[2:17], v[120:123], v[124:127], v[2:17]
	v_mfma_f32_32x32x16_bf16 v[50:65], v[112:115], v[116:119], v[50:65]
	v_mfma_f32_32x32x16_bf16 v[34:49], v[112:115], v[124:127], v[34:49]
	v_add_u32_e32 v120, v111, v109
	v_add_u32_e32 v124, v128, v109
	ds_read_b128 v[112:115], v120
	ds_read_b128 v[116:119], v124 offset:16384
	ds_read_b128 v[120:123], v120 offset:4096
	ds_read_b128 v[124:127], v124 offset:20480
	s_waitcnt lgkmcnt(4)
	v_mfma_f32_32x32x16_bf16 v[18:33], v[248:251], v[244:247], v[18:33]
	v_mfma_f32_32x32x16_bf16 v[2:17], v[248:251], v[252:255], v[2:17]
	v_mfma_f32_32x32x16_bf16 v[50:65], v[240:243], v[244:247], v[50:65]
	v_mfma_f32_32x32x16_bf16 v[34:49], v[240:243], v[252:255], v[34:49]
	v_add_u32_e32 v248, v111, v110
	v_add_u32_e32 v252, v128, v110
	ds_read_b128 v[240:243], v248
	ds_read_b128 v[244:247], v252 offset:16384
	ds_read_b128 v[248:251], v248 offset:4096
	ds_read_b128 v[252:255], v252 offset:20480
	s_waitcnt lgkmcnt(4)
	v_mfma_f32_32x32x16_bf16 v[18:33], v[120:123], v[116:119], v[18:33]
	v_mfma_f32_32x32x16_bf16 v[2:17], v[120:123], v[124:127], v[2:17]
	v_mfma_f32_32x32x16_bf16 v[50:65], v[112:115], v[116:119], v[50:65]
	v_mfma_f32_32x32x16_bf16 v[34:49], v[112:115], v[124:127], v[34:49]
	s_add_i32 s35, s35, 1
	s_waitcnt vmcnt(0) lgkmcnt(0)
	s_barrier
	v_mfma_f32_32x32x16_bf16 v[50:65], v[240:243], v[244:247], v[50:65]
	v_mfma_f32_32x32x16_bf16 v[34:49], v[240:243], v[252:255], v[34:49]
	v_mfma_f32_32x32x16_bf16 v[18:33], v[248:251], v[244:247], v[18:33]
	v_mfma_f32_32x32x16_bf16 v[2:17], v[248:251], v[252:255], v[2:17]
	s_mov_b32 s15, s17
	s_branch .Lkl5_top

; #define MFMA32(a, b, c) __builtin_amdgcn_mfma_f32_32x32x16_bf16((a), (b), (c), 0, 0, 0)
; #define GAS __attribute__((address_space(1)))
; DI void gemm_stage(const u16* __restrict__ A, int lda, const u16* __restrict__ B, int ldb, int kt, char* sbuf) {
;     ...
;   for (int i = 0; i < 4; i++) {
;     const int blk = i * 4 + wave;
;     const int p = blk * 4 + pp;
;     const int row = 2 * p + (pos >> 3), c8 = (pos & 7) ^ (p & 7);
;     const u16* ga = A + (size_t)row * lda + kt * 64 + c8 * 8;
;     const u16* gb = B + (size_t)row * ldb + kt * 64 + c8 * 8;
;     __builtin_amdgcn_global_load_lds((const GAS void*)ga, (__attribute__((address_space(3))) void*)(sbuf + blk * 1024), 16, 0, 0);
;     __builtin_amdgcn_global_load_lds((const GAS void*)gb, (__attribute__((address_space(3))) void*)(sbuf + 16384 + blk * 1024), 16, 0, 0);
;   }
; DI void gemm_main(f32x16 (&acc)[2][2], const u16* __restrict__ A, int lda, const u16* __restrict__ B, int ldb, int K, u16* sm) {
;     ...
;   for (int kt = 0; kt < nk; kt++) {
;     if (kt + 1 < nk) gemm_stage(A, lda, B, ldb, kt + 1, sb + ((kt + 1) & 1) * GST_);
;     const char* st = sb + (kt & 1) * GST_;
; #pragma unroll
;     for (int ks = 0; ks < 4; ks++) {
;       const int ca = ((ks * 2 + hh) ^ xa) << 4, cb = ((ks * 2 + hh) ^ xb) << 4;
;       const bf16x8 fa0 = *(const bf16x8*)(st + baseA + ca);
;       const bf16x8 fa1 = *(const bf16x8*)(st + baseA + 4096 + ca);
;       const bf16x8 fb0 = *(const bf16x8*)(st + baseB + cb);
;       const bf16x8 fb1 = *(const bf16x8*)(st + baseB + 4096 + cb);
;       acc[0][0] = MFMA32(fa0, fb0, acc[0][0]); acc[0][1] = MFMA32(fa0, fb1, acc[0][1]);
;       acc[1][0] = MFMA32(fa1, fb0, acc[1][0]); acc[1][1] = MFMA32(fa1, fb1, acc[1][1]);
;     }
;     asm volatile("s_waitcnt vmcnt(0)" ::: "memory");
;     __syncthreads();
;   }
.Lkl6_top:
	s_cmp_lt_u32 s28, 3
	s_cbranch_scc0 .Lkl6_last
	v_add_u32_e32 v92, s7, v69
	v_add3_u32 v93, s7, v70, v68
	v_add_u32_e32 v84, v92, v72
	v_add_u32_e32 v88, v93, v72
	ds_read_b128 v[76:79], v84
	ds_read_b128 v[80:83], v88 offset:16384
	ds_read_b128 v[84:87], v84 offset:4096
	ds_read_b128 v[88:91], v88 offset:20480
	v_add_u32_e32 v248, v92, v73
	v_add_u32_e32 v252, v93, v73
	ds_read_b128 v[240:243], v248
	ds_read_b128 v[244:247], v252 offset:16384
	ds_read_b128 v[248:251], v248 offset:4096
	ds_read_b128 v[252:255], v252 offset:20480
	s_xor_b32 s13, s7, 0x8000
	s_add_i32 m0, s13, s29
	global_load_lds_dwordx4 v238, s[4:5]
	s_add_i32 m0, m0, 0x1000
	s_nop 0
	global_load_lds_dwordx4 v239, s[4:5]
	s_add_i32 m0, m0, 0x1000
	s_nop 0
	global_load_lds_dwordx4 v238, s[10:11]
	s_add_i32 m0, m0, 0x1000
	s_nop 0
	global_load_lds_dwordx4 v239, s[10:11]
	s_add_i32 m0, m0, 0x1000
	s_nop 0
	global_load_lds_dwordx4 v238, s[8:9]
	s_add_i32 m0, m0, 0x1000
	s_nop 0
	global_load_lds_dwordx4 v239, s[8:9]
	s_add_i32 m0, m0, 0x1000
	s_nop 0
	global_load_lds_dwordx4 v238, s[14:15]
	s_add_i32 m0, m0, 0x1000
	s_nop 0
	global_load_lds_dwordx4 v239, s[14:15]
	s_nop 0
	v_add_u32_e32 v238, 0x80, v238
	v_add_u32_e32 v239, 0x80, v239
	s_waitcnt lgkmcnt(4)
	v_mfma_f32_32x32x16_bf16 v[18:33], v[84:87], v[80:83], v[18:33]
	v_mfma_f32_32x32x16_bf16 v[2:17], v[84:87], v[88:91], v[2:17]
	v_mfma_f32_32x32x16_bf16 v[50:65], v[76:79], v[80:83], v[50:65]
	v_mfma_f32_32x32x16_bf16 v[34:49], v[76:79], v[88:91], v[34:49]
	v_add_u32_e32 v84, v92, v74
	v_add_u32_e32 v88, v93, v74
	ds_read_b128 v[76:79], v84
	ds_read_b128 v[80:83], v88 offset:16384
	ds_read_b128 v[84:87], v84 offset:4096
	ds_read_b128 v[88:91], v88 offset:20480
	s_waitcnt lgkmcnt(4)
	v_mfma_f32_32x32x16_bf16 v[18:33], v[248:251], v[244:247], v[18:33]
	v_mfma_f32_32x32x16_bf16 v[2:17], v[248:251], v[252:255], v[2:17]
	v_mfma_f32_32x32x16_bf16 v[50:65], v[240:243], v[244:247], v[50:65]
	v_mfma_f32_32x32x16_bf16 v[34:49], v[240:243], v[252:255], v[34:49]
	v_add_u32_e32 v248, v92, v75
	v_add_u32_e32 v252, v93, v75
	ds_read_b128 v[240:243], v248
	ds_read_b128 v[244:247], v252 offset:16384
	ds_read_b128 v[248:251], v248 offset:4096
	ds_read_b128 v[252:255], v252 offset:20480
	s_waitcnt lgkmcnt(4)
	v_mfma_f32_32x32x16_bf16 v[18:33], v[84:87], v[80:83], v[18:33]
	v_mfma_f32_32x32x16_bf16 v[2:17], v[84:87], v[88:91], v[2:17]
	v_mfma_f32_32x32x16_bf16 v[50:65], v[76:79], v[80:83], v[50:65]
	v_mfma_f32_32x32x16_bf16 v[34:49], v[76:79], v[88:91], v[34:49]
	s_add_i32 s28, s28, 1
	s_waitcnt vmcnt(0) lgkmcnt(0)
	s_barrier
	v_mfma_f32_32x32x16_bf16 v[50:65], v[240:243], v[244:247], v[50:65]
	v_mfma_f32_32x32x16_bf16 v[34:49], v[240:243], v[252:255], v[34:49]
	v_mfma_f32_32x32x16_bf16 v[18:33], v[248:251], v[244:247], v[18:33]
	v_mfma_f32_32x32x16_bf16 v[2:17], v[248:251], v[252:255], v[2:17]
	s_mov_b32 s7, s13
	s_branch .Lkl6_top

; #define MFMA32(a, b, c) __builtin_amdgcn_mfma_f32_32x32x16_bf16((a), (b), (c), 0, 0, 0)
; #define GAS __attribute__((address_space(1)))
; DI void gemm_stage(const u16* __restrict__ A, int lda, const u16* __restrict__ B, int ldb, int kt, char* sbuf) {
;     ...
;   for (int i = 0; i < 4; i++) {
;     const int blk = i * 4 + wave;
;     const int p = blk * 4 + pp;
;     const int row = 2 * p + (pos >> 3), c8 = (pos & 7) ^ (p & 7);
;     const u16* ga = A + (size_t)row * lda + kt * 64 + c8 * 8;
;     const u16* gb = B + (size_t)row * ldb + kt * 64 + c8 * 8;
;     __builtin_amdgcn_global_load_lds((const GAS void*)ga, (__attribute__((address_space(3))) void*)(sbuf + blk * 1024), 16, 0, 0);
;     __builtin_amdgcn_global_load_lds((const GAS void*)gb, (__attribute__((address_space(3))) void*)(sbuf + 16384 + blk * 1024), 16, 0, 0);
;   }
; DI void gemm_main(f32x16 (&acc)[2][2], const u16* __restrict__ A, int lda, const u16* __restrict__ B, int ldb, int K, u16* sm) {
;     ...
;   for (int kt = 0; kt < nk; kt++) {
;     if (kt + 1 < nk) gemm_stage(A, lda, B, ldb, kt + 1, sb + ((kt + 1) & 1) * GST_);
;     const char* st = sb + (kt & 1) * GST_;
; #pragma unroll
;     for (int ks = 0; ks < 4; ks++) {
;       const int ca = ((ks * 2 + hh) ^ xa) << 4, cb = ((ks * 2 + hh) ^ xb) << 4;
;       const bf16x8 fa0 = *(const bf16x8*)(st + baseA + ca);
;       const bf16x8 fa1 = *(const bf16x8*)(st + baseA + 4096 + ca);
;       const bf16x8 fb0 = *(const bf16x8*)(st + baseB + cb);
;       const bf16x8 fb1 = *(const bf16x8*)(st + baseB + 4096 + cb);
;       acc[0][0] = MFMA32(fa0, fb0, acc[0][0]); acc[0][1] = MFMA32(fa0, fb1, acc[0][1]);
;       acc[1][0] = MFMA32(fa1, fb0, acc[1][0]); acc[1][1] = MFMA32(fa1, fb1, acc[1][1]);
;     }
;     asm volatile("s_waitcnt vmcnt(0)" ::: "memory");
;     __syncthreads();
;   }
.Lkl7_top:
	s_cmp_lt_u32 s38, 43
	s_cbranch_scc0 .Lkl7_last
	v_add_u32_e32 v188, s36, v166
	v_add3_u32 v189, s36, v167, v66
	v_add_u32_e32 v180, v188, v168
	v_add_u32_e32 v184, v189, v168
	ds_read_b128 v[172:175], v180
	ds_read_b128 v[176:179], v184 offset:16384
	ds_read_b128 v[180:183], v180 offset:4096
	ds_read_b128 v[184:187], v184 offset:20480
	v_add_u32_e32 v248, v188, v169
	v_add_u32_e32 v252, v189, v169
	ds_read_b128 v[240:243], v248
	ds_read_b128 v[244:247], v252 offset:16384
	ds_read_b128 v[248:251], v248 offset:4096
	ds_read_b128 v[252:255], v252 offset:20480
	s_xor_b32 s37, s36, 0x8000
	s_add_i32 m0, s37, s39
	global_load_lds_dwordx4 v238, s[14:15]
	s_add_i32 m0, m0, 0x1000
	s_nop 0
	global_load_lds_dwordx4 v239, s[14:15]
	s_add_i32 m0, m0, 0x1000
	s_nop 0
	global_load_lds_dwordx4 v238, s[18:19]
	s_add_i32 m0, m0, 0x1000
	s_nop 0
	global_load_lds_dwordx4 v239, s[18:19]
	s_add_i32 m0, m0, 0x1000
	s_nop 0
	global_load_lds_dwordx4 v238, s[16:17]
	s_add_i32 m0, m0, 0x1000
	s_nop 0
	global_load_lds_dwordx4 v239, s[16:17]
	s_add_i32 m0, m0, 0x1000
	s_nop 0
	global_load_lds_dwordx4 v238, s[20:21]
	s_add_i32 m0, m0, 0x1000
	s_nop 0
	global_load_lds_dwordx4 v239, s[20:21]
	s_nop 0
	v_add_u32_e32 v238, 0x80, v238
	v_add_u32_e32 v239, 0x80, v239
	s_waitcnt lgkmcnt(4)
	v_mfma_f32_32x32x16_bf16 v[34:49], v[180:183], v[176:179], v[34:49]
	v_mfma_f32_32x32x16_bf16 v[50:65], v[180:183], v[184:187], v[50:65]
	v_mfma_f32_32x32x16_bf16 v[2:17], v[172:175], v[176:179], v[2:17]
	v_mfma_f32_32x32x16_bf16 v[18:33], v[172:175], v[184:187], v[18:33]
	v_add_u32_e32 v180, v188, v170
	v_add_u32_e32 v184, v189, v170
	ds_read_b128 v[172:175], v180
	ds_read_b128 v[176:179], v184 offset:16384
	ds_read_b128 v[180:183], v180 offset:4096
	ds_read_b128 v[184:187], v184 offset:20480
	s_waitcnt lgkmcnt(4)
	v_mfma_f32_32x32x16_bf16 v[34:49], v[248:251], v[244:247], v[34:49]
	v_mfma_f32_32x32x16_bf16 v[50:65], v[248:251], v[252:255], v[50:65]
	v_mfma_f32_32x32x16_bf16 v[2:17], v[240:243], v[244:247], v[2:17]
	v_mfma_f32_32x32x16_bf16 v[18:33], v[240:243], v[252:255], v[18:33]
	v_add_u32_e32 v248, v188, v171
	v_add_u32_e32 v252, v189, v171
	ds_read_b128 v[240:243], v248
	ds_read_b128 v[244:247], v252 offset:16384
	ds_read_b128 v[248:251], v248 offset:4096
	ds_read_b128 v[252:255], v252 offset:20480
	s_waitcnt lgkmcnt(4)
	v_mfma_f32_32x32x16_bf16 v[34:49], v[180:183], v[176:179], v[34:49]
	v_mfma_f32_32x32x16_bf16 v[50:65], v[180:183], v[184:187], v[50:65]
	v_mfma_f32_32x32x16_bf16 v[2:17], v[172:175], v[176:179], v[2:17]
	v_mfma_f32_32x32x16_bf16 v[18:33], v[172:175], v[184:187], v[18:33]
	s_add_i32 s38, s38, 1
	s_waitcnt vmcnt(0) lgkmcnt(0)
	s_barrier
	v_mfma_f32_32x32x16_bf16 v[2:17], v[240:243], v[244:247], v[2:17]
	v_mfma_f32_32x32x16_bf16 v[18:33], v[240:243], v[252:255], v[18:33]
	v_mfma_f32_32x32x16_bf16 v[34:49], v[248:251], v[244:247], v[34:49]
	v_mfma_f32_32x32x16_bf16 v[50:65], v[248:251], v[252:255], v[50:65]
	s_mov_b32 s36, s37
	s_branch .Lkl7_top

; DI int tidx() { int t = threadIdx.x; asm volatile("" : "+v"(t)); return t; }
; #define GAS __attribute__((address_space(1)))
; DI void gemm_stage(const u16* __restrict__ A, int lda, const u16* __restrict__ B, int ldb, int kt, char* sbuf) {
;   const int tid = tidx(), lane = tid & 63, wave = __builtin_amdgcn_readfirstlane(tid >> 6);
;   const int pp = lane >> 4, pos = lane & 15;
; #pragma unroll
;   for (int i = 0; i < 4; i++) {
;     const int blk = i * 4 + wave;
;     const int p = blk * 4 + pp;
;     const int row = 2 * p + (pos >> 3), c8 = (pos & 7) ^ (p & 7);
;     const u16* ga = A + (size_t)row * lda + kt * 64 + c8 * 8;
;     const u16* gb = B + (size_t)row * ldb + kt * 64 + c8 * 8;
;     __builtin_amdgcn_global_load_lds((const GAS void*)ga, (__attribute__((address_space(3))) void*)(sbuf + blk * 1024), 16, 0, 0);
;     __builtin_amdgcn_global_load_lds((const GAS void*)gb, (__attribute__((address_space(3))) void*)(sbuf + 16384 + blk * 1024), 16, 0, 0);
;   }
; }
; template <class AF, class BF, class INI, class EPI>
; DI void gemm_phase_init(int TM, int TN, int K, int lda, int ldb, AF a_of, BF b_of, INI ini, EPI epi, int bid, int nb, u16* sm) {
;   int tm, tn;
;   bool have = tile_at(0, bid, nb, TM, TN, tm, tn);
;   __syncthreads();
;   if (have) gemm_stage(a_of(tm), lda, b_of(tn), ldb, 0, (char*)sm);
.LBB0_4891:
	s_andn2_b64 vcc, exec, s[10:11]
	s_waitcnt vmcnt(0) lgkmcnt(0)
	s_barrier
	s_cbranch_vccnz .LBB0_4910
	v_readlane_b32 s10, v237, 0
	v_readlane_b32 s11, v237, 1
	s_add_u32 s14, s10, s4
	s_addc_u32 s15, s11, s5
	s_add_u32 s3, s14, 0x558d140
	s_addc_u32 s18, s15, 0
	s_add_u32 s4, s14, 0x1158d140
	s_addc_u32 s5, s15, 0
	s_add_u32 s19, s14, 0xb00000
	s_addc_u32 s20, s15, 0
	s_ashr_i32 s9, s8, 31
	s_lshl_b64 s[10:11], s[8:9], 18
	s_add_u32 s10, s3, s10
	s_addc_u32 s11, s18, s11
	s_ashr_i32 s7, s6, 31
	s_lshl_b64 s[12:13], s[6:7], 18
	v_mov_b32_e32 v1, v202
	s_add_u32 s12, s19, s12
	s_addc_u32 s13, s20, s13
	v_readfirstlane_b32 s7, v1
	s_ashr_i32 s7, s7, 6
	v_bfe_u32 v8, v1, 4, 2
	s_lshl_b32 s9, s7, 2
	v_bfe_u32 v9, v1, 3, 1
	v_or_b32_e32 v4, s9, v8
	v_lshl_or_b32 v4, v4, 1, v9
	v_bitop3_b32 v10, s9, v1, v8 bitop3:0x36
	v_ashrrev_i32_e32 v5, 31, v4
	v_lshlrev_b64 v[4:5], 11, v[4:5]
	v_lshlrev_b32_e32 v10, 4, v10
	s_lshl_b32 s9, s7, 10
	v_lshl_add_u64 v[6:7], s[10:11], 0, v[4:5]
	v_and_b32_e32 v66, 0x70, v10
	v_mov_b32_e32 v67, 0
	s_add_i32 s9, s9, 0
	v_lshl_add_u64 v[6:7], v[6:7], 0, v[66:67]
	s_mov_b32 m0, s9
	v_lshl_add_u64 v[4:5], s[12:13], 0, v[4:5]
	global_load_lds_dwordx4 v[6:7], off
	s_add_i32 m0, s9, 0x4000
	s_add_i32 s9, s7, 4
	v_lshl_add_u64 v[4:5], v[4:5], 0, v[66:67]
	s_lshl_b32 s16, s9, 2
	global_load_lds_dwordx4 v[4:5], off
	v_or_b32_e32 v4, s16, v8
	v_lshl_or_b32 v4, v4, 1, v9
	v_bitop3_b32 v10, s16, v1, v8 bitop3:0x36
	v_ashrrev_i32_e32 v5, 31, v4
	v_lshlrev_b64 v[4:5], 11, v[4:5]
	v_lshlrev_b32_e32 v10, 4, v10
	s_lshl_b32 s9, s9, 10
	v_lshl_add_u64 v[6:7], s[10:11], 0, v[4:5]
	v_and_b32_e32 v66, 0x70, v10
	s_add_i32 s9, s9, 0
	v_lshl_add_u64 v[6:7], v[6:7], 0, v[66:67]
	s_mov_b32 m0, s9
	v_lshl_add_u64 v[4:5], s[12:13], 0, v[4:5]
	global_load_lds_dwordx4 v[6:7], off
	s_add_i32 m0, s9, 0x4000
	s_add_i32 s9, s7, 8
	v_lshl_add_u64 v[4:5], v[4:5], 0, v[66:67]
	s_lshl_b32 s16, s9, 2
	global_load_lds_dwordx4 v[4:5], off
	v_or_b32_e32 v4, s16, v8
	v_lshl_or_b32 v4, v4, 1, v9
	v_bitop3_b32 v10, s16, v1, v8 bitop3:0x36
	v_ashrrev_i32_e32 v5, 31, v4
	v_lshlrev_b64 v[4:5], 11, v[4:5]
	v_lshlrev_b32_e32 v10, 4, v10
	s_lshl_b32 s9, s9, 10
	v_lshl_add_u64 v[6:7], s[10:11], 0, v[4:5]
	v_and_b32_e32 v66, 0x70, v10
	s_add_i32 s9, s9, 0
	v_lshl_add_u64 v[6:7], v[6:7], 0, v[66:67]
	v_lshl_add_u64 v[4:5], s[12:13], 0, v[4:5]
	s_mov_b32 m0, s9
	s_add_i32 s7, s7, 12
	v_lshl_add_u64 v[4:5], v[4:5], 0, v[66:67]
	global_load_lds_dwordx4 v[6:7], off
	s_add_i32 m0, s9, 0x4000
	s_lshl_b32 s9, s7, 2
	global_load_lds_dwordx4 v[4:5], off
	v_or_b32_e32 v4, s9, v8
	v_lshl_or_b32 v4, v4, 1, v9
	v_bitop3_b32 v1, s9, v1, v8 bitop3:0x36
	v_ashrrev_i32_e32 v5, 31, v4
	v_lshlrev_b64 v[4:5], 11, v[4:5]
	v_lshlrev_b32_e32 v1, 4, v1
	s_lshl_b32 s7, s7, 10
	v_lshl_add_u64 v[6:7], s[10:11], 0, v[4:5]
	v_and_b32_e32 v66, 0x70, v1
	s_add_i32 s7, s7, 0
	v_lshl_add_u64 v[6:7], v[6:7], 0, v[66:67]
	v_lshl_add_u64 v[4:5], s[12:13], 0, v[4:5]
	s_mov_b32 m0, s7
	v_lshl_add_u64 v[4:5], v[4:5], 0, v[66:67]
	global_load_lds_dwordx4 v[6:7], off
	s_add_i32 m0, s7, 0x4000
	s_lshl_b32 s7, s2, 6
	global_load_lds_dwordx4 v[4:5], off
	v_lshrrev_b32_e32 v1, 1, v3
	s_ashr_i32 s22, s2, 3
	s_ashr_i32 s23, s94, 3
	s_and_b32 s24, s7, 0x1c0
	v_and_b32_e32 v1, 32, v1
	v_and_or_b32 v1, v2, 31, v1
	v_lshrrev_b32_e32 v2, 3, v2
	s_add_u32 s25, s14, 0x558d1c0
	v_ashrrev_i32_e32 v3, 1, v3
	v_and_b32_e32 v2, 4, v2
	s_movk_i32 s7, 0xffc0
	s_addc_u32 s26, s15, 0
	v_and_or_b32 v70, v3, s7, v2
	s_add_u32 s27, s14, 0xb00080
	s_mov_b32 s21, 0
	v_or_b32_e32 v71, 1, v70
	v_or_b32_e32 v72, 2, v70
	v_or_b32_e32 v73, 3, v70
	v_or_b32_e32 v74, 8, v70
	v_or_b32_e32 v75, 9, v70
	v_or_b32_e32 v76, 10, v70
	v_or_b32_e32 v77, 11, v70
	v_or_b32_e32 v78, 16, v70
	v_or_b32_e32 v79, 17, v70
	v_or_b32_e32 v80, 18, v70
	v_or_b32_e32 v81, 19, v70
	v_or_b32_e32 v82, 24, v70
	v_or_b32_e32 v83, 25, v70
	v_or_b32_e32 v84, 26, v70
	v_or_b32_e32 v85, 27, v70
	v_or_b32_e32 v86, 32, v70
	v_or_b32_e32 v87, 33, v70
	v_or_b32_e32 v88, 34, v70
	v_or_b32_e32 v89, 35, v70
	v_or_b32_e32 v90, 40, v70
	v_or_b32_e32 v91, 41, v70
	v_or_b32_e32 v92, 42, v70
	v_or_b32_e32 v93, 43, v70
	v_or_b32_e32 v94, 48, v70
	v_or_b32_e32 v95, 49, v70
	v_or_b32_e32 v96, 50, v70
	v_or_b32_e32 v97, 51, v70
	v_or_b32_e32 v98, 56, v70
	v_or_b32_e32 v99, 57, v70
	v_or_b32_e32 v100, 58, v70
	v_or_b32_e32 v101, 59, v70
	s_addc_u32 s28, s15, 0
	s_mov_b32 s29, 0x1ffffc0
	s_movk_i32 s30, 0x1600
	s_waitcnt vmcnt(0)
	s_branch .LBB0_4894

; #define MFMA32(a, b, c) __builtin_amdgcn_mfma_f32_32x32x16_bf16((a), (b), (c), 0, 0, 0)
; DI int tidx() { int t = threadIdx.x; asm volatile("" : "+v"(t)); return t; }
; #define GAS __attribute__((address_space(1)))
; DI void gemm_stage(const u16* __restrict__ A, int lda, const u16* __restrict__ B, int ldb, int kt, char* sbuf) {
;   const int tid = tidx(), lane = tid & 63, wave = __builtin_amdgcn_readfirstlane(tid >> 6);
;   const int pp = lane >> 4, pos = lane & 15;
; #pragma unroll
;   for (int i = 0; i < 4; i++) {
;     const int blk = i * 4 + wave;
;     const int p = blk * 4 + pp;
;     const int row = 2 * p + (pos >> 3), c8 = (pos & 7) ^ (p & 7);
;     const u16* ga = A + (size_t)row * lda + kt * 64 + c8 * 8;
;     const u16* gb = B + (size_t)row * ldb + kt * 64 + c8 * 8;
;     __builtin_amdgcn_global_load_lds((const GAS void*)ga, (__attribute__((address_space(3))) void*)(sbuf + blk * 1024), 16, 0, 0);
;     __builtin_amdgcn_global_load_lds((const GAS void*)gb, (__attribute__((address_space(3))) void*)(sbuf + 16384 + blk * 1024), 16, 0, 0);
;   }
; DI void gemm_main(f32x16 (&acc)[2][2], const u16* __restrict__ A, int lda, const u16* __restrict__ B, int ldb, int K, u16* sm) {
;     ...
;   for (int kt = 0; kt < nk; kt++) {
;     if (kt + 1 < nk) gemm_stage(A, lda, B, ldb, kt + 1, sb + ((kt + 1) & 1) * GST_);
;     const char* st = sb + (kt & 1) * GST_;
; #pragma unroll
;     for (int ks = 0; ks < 4; ks++) {
;       const int ca = ((ks * 2 + hh) ^ xa) << 4, cb = ((ks * 2 + hh) ^ xb) << 4;
;       const bf16x8 fa0 = *(const bf16x8*)(st + baseA + ca);
;       const bf16x8 fa1 = *(const bf16x8*)(st + baseA + 4096 + ca);
;       const bf16x8 fb0 = *(const bf16x8*)(st + baseB + cb);
;       const bf16x8 fb1 = *(const bf16x8*)(st + baseB + 4096 + cb);
;       acc[0][0] = MFMA32(fa0, fb0, acc[0][0]); acc[0][1] = MFMA32(fa0, fb1, acc[0][1]);
;       acc[1][0] = MFMA32(fa1, fb0, acc[1][0]); acc[1][1] = MFMA32(fa1, fb1, acc[1][1]);
;     }
;     asm volatile("s_waitcnt vmcnt(0)" ::: "memory");
;     __syncthreads();
;   }
.Lkl9_top:
	s_cmp_lt_u32 s33, 43
	s_cbranch_scc0 .Lkl9_last
	v_add_u32_e32 v188, s30, v166
	v_add3_u32 v189, s30, v167, v66
	v_add_u32_e32 v180, v188, v168
	v_add_u32_e32 v184, v189, v168
	ds_read_b128 v[172:175], v180
	ds_read_b128 v[176:179], v184 offset:16384
	ds_read_b128 v[180:183], v180 offset:4096
	ds_read_b128 v[184:187], v184 offset:20480
	v_add_u32_e32 v248, v188, v169
	v_add_u32_e32 v252, v189, v169
	ds_read_b128 v[240:243], v248
	ds_read_b128 v[244:247], v252 offset:16384
	ds_read_b128 v[248:251], v248 offset:4096
	ds_read_b128 v[252:255], v252 offset:20480
	s_xor_b32 s31, s30, 0x8000
	s_add_i32 m0, s31, s34
	global_load_lds_dwordx4 v238, s[10:11]
	s_add_i32 m0, m0, 0x1000
	s_nop 0
	global_load_lds_dwordx4 v239, s[10:11]
	s_add_i32 m0, m0, 0x1000
	s_nop 0
	global_load_lds_dwordx4 v238, s[14:15]
	s_add_i32 m0, m0, 0x1000
	s_nop 0
	global_load_lds_dwordx4 v239, s[14:15]
	s_add_i32 m0, m0, 0x1000
	s_nop 0
	global_load_lds_dwordx4 v238, s[12:13]
	s_add_i32 m0, m0, 0x1000
	s_nop 0
	global_load_lds_dwordx4 v239, s[12:13]
	s_add_i32 m0, m0, 0x1000
	s_nop 0
	global_load_lds_dwordx4 v238, s[16:17]
	s_add_i32 m0, m0, 0x1000
	s_nop 0
	global_load_lds_dwordx4 v239, s[16:17]
	s_nop 0
	v_add_u32_e32 v238, 0x80, v238
	v_add_u32_e32 v239, 0x80, v239
	s_waitcnt lgkmcnt(4)
	v_mfma_f32_32x32x16_bf16 v[34:49], v[180:183], v[176:179], v[34:49]
	v_mfma_f32_32x32x16_bf16 v[18:33], v[180:183], v[184:187], v[18:33]
	v_mfma_f32_32x32x16_bf16 v[2:17], v[172:175], v[176:179], v[2:17]
	v_mfma_f32_32x32x16_bf16 v[50:65], v[172:175], v[184:187], v[50:65]
	v_add_u32_e32 v180, v188, v170
	v_add_u32_e32 v184, v189, v170
	ds_read_b128 v[172:175], v180
	ds_read_b128 v[176:179], v184 offset:16384
	ds_read_b128 v[180:183], v180 offset:4096
	ds_read_b128 v[184:187], v184 offset:20480
	s_waitcnt lgkmcnt(4)
	v_mfma_f32_32x32x16_bf16 v[34:49], v[248:251], v[244:247], v[34:49]
	v_mfma_f32_32x32x16_bf16 v[18:33], v[248:251], v[252:255], v[18:33]
	v_mfma_f32_32x32x16_bf16 v[2:17], v[240:243], v[244:247], v[2:17]
	v_mfma_f32_32x32x16_bf16 v[50:65], v[240:243], v[252:255], v[50:65]
	v_add_u32_e32 v248, v188, v171
	v_add_u32_e32 v252, v189, v171
	ds_read_b128 v[240:243], v248
	ds_read_b128 v[244:247], v252 offset:16384
	ds_read_b128 v[248:251], v248 offset:4096
	ds_read_b128 v[252:255], v252 offset:20480
	s_waitcnt lgkmcnt(4)
	v_mfma_f32_32x32x16_bf16 v[34:49], v[180:183], v[176:179], v[34:49]
	v_mfma_f32_32x32x16_bf16 v[18:33], v[180:183], v[184:187], v[18:33]
	v_mfma_f32_32x32x16_bf16 v[2:17], v[172:175], v[176:179], v[2:17]
	v_mfma_f32_32x32x16_bf16 v[50:65], v[172:175], v[184:187], v[50:65]
	s_add_i32 s33, s33, 1
	s_waitcnt vmcnt(0) lgkmcnt(0)
	s_barrier
	v_mfma_f32_32x32x16_bf16 v[2:17], v[240:243], v[244:247], v[2:17]
	v_mfma_f32_32x32x16_bf16 v[50:65], v[240:243], v[252:255], v[50:65]
	v_mfma_f32_32x32x16_bf16 v[34:49], v[248:251], v[244:247], v[34:49]
	v_mfma_f32_32x32x16_bf16 v[18:33], v[248:251], v[252:255], v[18:33]
	s_mov_b32 s30, s31
	s_branch .Lkl9_top

; DI int tidx() { int t = threadIdx.x; asm volatile("" : "+v"(t)); return t; }
; #define GAS __attribute__((address_space(1)))
; DI void gemm_stage(const u16* __restrict__ A, int lda, const u16* __restrict__ B, int ldb, int kt, char* sbuf) {
;   const int tid = tidx(), lane = tid & 63, wave = __builtin_amdgcn_readfirstlane(tid >> 6);
;   const int pp = lane >> 4, pos = lane & 15;
; #pragma unroll
;   for (int i = 0; i < 4; i++) {
;     const int blk = i * 4 + wave;
;     const int p = blk * 4 + pp;
;     const int row = 2 * p + (pos >> 3), c8 = (pos & 7) ^ (p & 7);
;     const u16* ga = A + (size_t)row * lda + kt * 64 + c8 * 8;
;     const u16* gb = B + (size_t)row * ldb + kt * 64 + c8 * 8;
;     __builtin_amdgcn_global_load_lds((const GAS void*)ga, (__attribute__((address_space(3))) void*)(sbuf + blk * 1024), 16, 0, 0);
;     __builtin_amdgcn_global_load_lds((const GAS void*)gb, (__attribute__((address_space(3))) void*)(sbuf + 16384 + blk * 1024), 16, 0, 0);
;   }
; template <class AF, class BF, class INI, class EPI>
; DI void gemm_phase_init(int TM, int TN, int K, int lda, int ldb, AF a_of, BF b_of, INI ini, EPI epi, int bid, int nb, u16* sm) {
;   int tm, tn;
;   bool have = tile_at(0, bid, nb, TM, TN, tm, tn);
;   __syncthreads();
;   if (have) gemm_stage(a_of(tm), lda, b_of(tn), ldb, 0, (char*)sm);
.LBB0_8532:
	v_readlane_b32 s12, v237, 0
	v_readlane_b32 s13, v237, 1
	s_add_u32 s3, s12, s4
	s_addc_u32 s20, s13, s5
	s_add_u32 s21, s3, 0x558d140
	s_addc_u32 s22, s20, 0
	s_andn2_b64 vcc, exec, s[6:7]
	s_waitcnt vmcnt(0) lgkmcnt(0)
	s_barrier
	s_cbranch_vccnz .LBB0_8551
	s_add_u32 s6, s3, 0x1158d140
	s_addc_u32 s7, s20, 0
	s_add_u32 s23, s3, 0x2c00000
	s_addc_u32 s24, s20, 0
	s_ashr_i32 s11, s10, 31
	s_lshl_b64 s[12:13], s[10:11], 18
	s_add_u32 s12, s21, s12
	s_addc_u32 s13, s22, s13
	s_ashr_i32 s9, s8, 31
	s_lshl_b64 s[14:15], s[8:9], 18
	v_mov_b32_e32 v1, v202
	s_add_u32 s14, s23, s14
	s_addc_u32 s15, s24, s15
	v_readfirstlane_b32 s9, v1
	s_ashr_i32 s9, s9, 6
	v_bfe_u32 v8, v1, 4, 2
	s_lshl_b32 s11, s9, 2
	v_bfe_u32 v9, v1, 3, 1
	v_or_b32_e32 v4, s11, v8
	v_lshl_or_b32 v4, v4, 1, v9
	v_bitop3_b32 v10, s11, v1, v8 bitop3:0x36
	v_ashrrev_i32_e32 v5, 31, v4
	v_lshlrev_b64 v[4:5], 11, v[4:5]
	v_lshlrev_b32_e32 v10, 4, v10
	s_lshl_b32 s11, s9, 10
	v_lshl_add_u64 v[6:7], s[12:13], 0, v[4:5]
	v_and_b32_e32 v66, 0x70, v10
	v_mov_b32_e32 v67, 0
	s_add_i32 s11, s11, 0
	v_lshl_add_u64 v[6:7], v[6:7], 0, v[66:67]
	s_mov_b32 m0, s11
	v_lshl_add_u64 v[4:5], s[14:15], 0, v[4:5]
	global_load_lds_dwordx4 v[6:7], off
	s_add_i32 m0, s11, 0x4000
	s_add_i32 s11, s9, 4
	v_lshl_add_u64 v[4:5], v[4:5], 0, v[66:67]
	s_lshl_b32 s16, s11, 2
	global_load_lds_dwordx4 v[4:5], off
	v_or_b32_e32 v4, s16, v8
	v_lshl_or_b32 v4, v4, 1, v9
	v_bitop3_b32 v10, s16, v1, v8 bitop3:0x36
	v_ashrrev_i32_e32 v5, 31, v4
	v_lshlrev_b64 v[4:5], 11, v[4:5]
	v_lshlrev_b32_e32 v10, 4, v10
	s_lshl_b32 s11, s11, 10
	v_lshl_add_u64 v[6:7], s[12:13], 0, v[4:5]
	v_and_b32_e32 v66, 0x70, v10
	s_add_i32 s11, s11, 0
	v_lshl_add_u64 v[6:7], v[6:7], 0, v[66:67]
	s_mov_b32 m0, s11
	v_lshl_add_u64 v[4:5], s[14:15], 0, v[4:5]
	global_load_lds_dwordx4 v[6:7], off
	s_add_i32 m0, s11, 0x4000
	s_add_i32 s11, s9, 8
	v_lshl_add_u64 v[4:5], v[4:5], 0, v[66:67]
	s_lshl_b32 s16, s11, 2
	global_load_lds_dwordx4 v[4:5], off
	v_or_b32_e32 v4, s16, v8
	v_lshl_or_b32 v4, v4, 1, v9
	v_bitop3_b32 v10, s16, v1, v8 bitop3:0x36
	v_ashrrev_i32_e32 v5, 31, v4
	v_lshlrev_b64 v[4:5], 11, v[4:5]
	v_lshlrev_b32_e32 v10, 4, v10
	s_lshl_b32 s11, s11, 10
	v_lshl_add_u64 v[6:7], s[12:13], 0, v[4:5]
	v_and_b32_e32 v66, 0x70, v10
	s_add_i32 s11, s11, 0
	v_lshl_add_u64 v[6:7], v[6:7], 0, v[66:67]
	v_lshl_add_u64 v[4:5], s[14:15], 0, v[4:5]
	s_mov_b32 m0, s11
	s_add_i32 s9, s9, 12
	v_lshl_add_u64 v[4:5], v[4:5], 0, v[66:67]
	global_load_lds_dwordx4 v[6:7], off
	s_add_i32 m0, s11, 0x4000
	s_lshl_b32 s11, s9, 2
	global_load_lds_dwordx4 v[4:5], off
	v_or_b32_e32 v4, s11, v8
	v_lshl_or_b32 v4, v4, 1, v9
	v_bitop3_b32 v1, s11, v1, v8 bitop3:0x36
	v_ashrrev_i32_e32 v5, 31, v4
	v_lshlrev_b64 v[4:5], 11, v[4:5]
	v_lshlrev_b32_e32 v1, 4, v1
	s_lshl_b32 s9, s9, 10
	v_lshl_add_u64 v[6:7], s[12:13], 0, v[4:5]
	v_and_b32_e32 v66, 0x70, v1
	s_add_i32 s9, s9, 0
	v_lshl_add_u64 v[6:7], v[6:7], 0, v[66:67]
	v_lshl_add_u64 v[4:5], s[14:15], 0, v[4:5]
	s_mov_b32 m0, s9
	v_lshl_add_u64 v[4:5], v[4:5], 0, v[66:67]
	global_load_lds_dwordx4 v[6:7], off
	s_add_i32 m0, s9, 0x4000
	v_lshrrev_b32_e32 v1, 1, v3
	global_load_lds_dwordx4 v[4:5], off
	v_and_b32_e32 v1, 32, v1
	s_lshl_b32 s9, s2, 6
	v_and_or_b32 v1, v2, 31, v1
	v_lshrrev_b32_e32 v2, 3, v2
	s_ashr_i32 s26, s2, 3
	s_ashr_i32 s27, s94, 3
	s_and_b32 s28, s9, 0x1c0
	v_ashrrev_i32_e32 v3, 1, v3
	v_and_b32_e32 v2, 4, v2
	s_movk_i32 s9, 0xffc0
	v_readlane_b32 s12, v237, 0
	v_and_or_b32 v70, v3, s9, v2
	v_readlane_b32 s13, v237, 1
	s_add_u32 s9, s12, s4
	s_addc_u32 s11, s13, s5
	s_add_u32 s29, s9, 0x558d1c0
	s_addc_u32 s30, s11, 0
	s_add_u32 s31, s9, 0x2c00080
	s_mov_b32 s25, 0
	v_or_b32_e32 v71, 1, v70
	v_or_b32_e32 v72, 2, v70
	v_or_b32_e32 v73, 3, v70
	v_or_b32_e32 v74, 8, v70
	v_or_b32_e32 v75, 9, v70
	v_or_b32_e32 v76, 10, v70
	v_or_b32_e32 v77, 11, v70
	v_or_b32_e32 v78, 16, v70
	v_or_b32_e32 v79, 17, v70
	v_or_b32_e32 v80, 18, v70
	v_or_b32_e32 v81, 19, v70
	v_or_b32_e32 v82, 24, v70
	v_or_b32_e32 v83, 25, v70
	v_or_b32_e32 v84, 26, v70
	v_or_b32_e32 v85, 27, v70
	v_or_b32_e32 v86, 32, v70
	v_or_b32_e32 v87, 33, v70
	v_or_b32_e32 v88, 34, v70
	v_or_b32_e32 v89, 35, v70
	v_or_b32_e32 v90, 40, v70
	v_or_b32_e32 v91, 41, v70
	v_or_b32_e32 v92, 42, v70
	v_or_b32_e32 v93, 43, v70
	v_or_b32_e32 v94, 48, v70
	v_or_b32_e32 v95, 49, v70
	v_or_b32_e32 v96, 50, v70
	v_or_b32_e32 v97, 51, v70
	v_or_b32_e32 v98, 56, v70
	v_or_b32_e32 v99, 57, v70
	v_or_b32_e32 v100, 58, v70
	v_or_b32_e32 v101, 59, v70
	s_addc_u32 s33, s11, 0
	s_mov_b32 s34, 0x1ffffc0
	s_movk_i32 s35, 0x1600
	s_waitcnt vmcnt(0)
	s_branch .LBB0_8535
